# lru_m1 conv rounds: dropped six waits that only drained LDS writes (no vector loads are outstanding there any more)
# speedup vs baseline: 1.0041x; 1.0041x over previous
; __device__ __forceinline__ void ld8bf(const bf16_t* p, float (&o)[8]) { unpack8(*(const u32x4*)p, o); }
; __device__ __forceinline__ const float* in_ptr(const Args& a, int i) { asm volatile("" : "+s"(i)); return a.in[i]; }
; __device__ __forceinline__ void w_lru_m1(const Args& a, int l, unsigned char* ws, const bf16_t* proj, bf16_t* y, LAS unsigned char* wl, int b, int ck_, int h, int lane) {
;     ...
;     const float* cw = in_ptr(a, I_LCW) + (size_t)l * 4 * 512; const float* cbias = in_ptr(a, I_LCB) + l * 512;
;     const bf16_t* gwt = (const bf16_t*)(ws + WS_GATE) + (size_t)l * 65536;
;     const bf16_t* waT = gwt + h * 4096; const bf16_t* wxT = gwt + 32768 + h * 4096;
;     const float* ba = in_ptr(a, I_BA) + l * 512 + 64 * h; const float* bx = in_ptr(a, I_BX) + l * 512 + 64 * h; const float* lam = in_ptr(a, I_LAM) + l * 512 + 64 * h;
;     bf16x8 nWa[2], nWx[2]; f32x4 nba, nbx, nlam;
; #pragma unroll
;     for (int kk = 0; kk < 2; ++kk) { nWa[kk] = *(const bf16x8*)(waT + lo * 64 + 32 * kk + 8 * fq); nWx[kk] = *(const bf16x8*)(wxT + lo * 64 + 32 * kk + 8 * fq); }
;     nba = *(const f32x4*)(ba + 4 * fq); nbx = *(const f32x4*)(bx + 4 * fq); nlam = *(const f32x4*)(lam + 4 * fq);
;     bf16x8 Xf[4][2];
; #pragma unroll
;     for (int kk = 0; kk < 2; ++kk) { const int ch0 = 64 * h + 32 * kk + 8 * fq; float w[4][8], bs[8];
; #pragma unroll
;         for (int j = 0; j < 8; ++j) { bs[j] = cbias[ch0 + j];
; #pragma unroll
;             for (int k = 0; k < 4; ++k) w[k][j] = cw[k * 512 + ch0 + j]; }
; #pragma unroll
;         for (int tb = 0; tb < 4; ++tb) { const int tok = 16 * tb + lo, t = 64 * ck_ + tok; float s[8];
; #pragma unroll
;             for (int j = 0; j < 8; ++j) s[j] = bs[j];
; #pragma unroll
;             for (int k = 0; k < 4; ++k) { const int tt = t - 3 + k; float x[8];
;                 ld8bf(proj + (size_t)(b * SEQ + (tt >= 0 ? tt : 0)) * NIN + C_LX + ch0, x);
.LBB0_520:
	s_lshr_b32 s20, s24, 8
	s_lshr_b32 s21, s24, 9
	s_add_i32 s20, s20, s24
	s_and_b32 s21, s21, 12
	s_add_i32 s20, s20, s21
	s_and_b32 s91, s20, 15
	s_cmp_gt_u32 s91, 7
	s_cbranch_scc1 .LBB0_519
	s_ashr_i32 s20, s24, 31
	s_ashr_i32 s90, s24, 4
	s_lshr_b32 s20, s20, 25
	s_add_i32 s27, s90, s20
	s_and_b32 s20, s27, 0xffffff80
	v_mov_b32_e32 v122, v144
	s_mov_b32 s34, 3
	s_sub_i32 s46, s90, s20
	s_ashr_i32 s35, s34, 31
	s_lshl_b32 s20, s46, 6
	s_lshl_b64 s[34:35], s[34:35], 3
	s_add_u32 s34, s0, s34
	s_addc_u32 s35, s1, s35
	s_load_dwordx2 s[40:41], s[34:35], 0x0
	s_mov_b32 s34, 4
	s_ashr_i32 s35, s34, 31
	s_lshl_b64 s[34:35], s[34:35], 3
	s_add_u32 s34, s0, s34
	s_addc_u32 s35, s1, s35
	s_lshl_b32 s21, s91, 13
	s_add_u32 s92, s2, s21
	s_addc_u32 s93, s3, 0
	s_load_dwordx2 s[42:43], s[34:35], 0x0
	s_add_u32 s34, s68, s21
	s_mov_b32 s44, 6
	s_addc_u32 s35, s70, 0
	s_ashr_i32 s45, s44, 31
	s_lshl_b64 s[44:45], s[44:45], 3
	s_add_u32 s44, s0, s44
	s_addc_u32 s45, s1, s45
	s_waitcnt lgkmcnt(0)
	s_mov_b32 s48, 8
	s_load_dwordx2 s[44:45], s[44:45], 0x0
	s_ashr_i32 s49, s48, 31
	s_lshl_b32 s21, s91, 6
	s_lshl_b64 s[48:49], s[48:49], 3
	s_add_u32 s48, s0, s48
	s_addc_u32 s49, s1, s49
	s_load_dwordx2 s[48:49], s[48:49], 0x0
	v_ashrrev_i32_e32 v8, 4, v122
	v_and_b32_e32 v136, 15, v122
	v_lshlrev_b32_e32 v4, 3, v8
	v_lshlrev_b32_e32 v2, 7, v136
	s_waitcnt lgkmcnt(0)
	s_add_u32 s47, s48, s88
	s_mov_b32 s48, 9
	s_addc_u32 s50, s49, s89
	s_ashr_i32 s49, s48, 31
	s_lshl_b64 s[48:49], s[48:49], 3
	s_add_u32 s48, s0, s48
	s_addc_u32 s49, s1, s49
	s_add_u32 s48, s78, 0x3b00000
	s_addc_u32 s49, s79, 0x0
	v_ashrrev_i32_e32 v5, 31, v4
	v_lshl_add_u64 v[0:1], s[92:93], 0, v[2:3]
	v_lshlrev_b64 v[100:101], 1, v[4:5]
	v_lshl_add_u64 v[0:1], v[0:1], 0, v[100:101]
	s_waitcnt lgkmcnt(0)
	s_add_u32 s51, s48, s88
	s_addc_u32 s52, s49, s89
	s_lshl_b32 s27, s27, 6
	s_and_b32 s27, s27, 0xffffe000
	s_add_u32 s48, s40, s96
	s_addc_u32 s49, s41, s97
	s_add_u32 s42, s42, s88
	s_addc_u32 s43, s43, s89
	s_add_u32 s40, s44, s88
	s_addc_u32 s41, s45, s89
	s_lshl_b32 s53, s91, 8
	s_add_u32 s40, s40, s53
	v_lshl_add_u64 v[6:7], s[34:35], 0, v[2:3]
	s_addc_u32 s41, s41, 0
	v_lshl_add_u64 v[6:7], v[6:7], 0, v[100:101]
	global_load_dwordx4 v[52:55], v[0:1], off
	global_load_dwordx4 v[56:59], v[6:7], off
	global_load_dwordx4 v[60:63], v[0:1], off offset:64
	global_load_dwordx4 v[64:67], v[6:7], off offset:64
	s_add_u32 s44, s47, s53
	v_lshlrev_b32_e32 v0, 2, v8
	s_addc_u32 s45, s50, 0
	v_ashrrev_i32_e32 v1, 31, v0
	s_add_u32 s50, s51, s53
	v_lshlrev_b64 v[6:7], 2, v[0:1]
	s_addc_u32 s51, s52, 0
	v_lshl_add_u64 v[108:109], s[40:41], 0, v[6:7]
	s_add_i32 s40, s20, -3
	v_add_u32_e32 v78, s21, v4
	v_lshl_add_u64 v[110:111], s[44:45], 0, v[6:7]
	v_lshl_add_u64 v[112:113], s[50:51], 0, v[6:7]
	v_ashrrev_i32_e32 v79, 31, v78
	v_add_u32_e32 v6, s40, v136
	v_lshlrev_b64 v[4:5], 2, v[78:79]
	v_cmp_lt_i32_e64 s[50:51], -1, v6
	v_lshl_add_u64 v[76:77], s[42:43], 0, v[4:5]
	v_lshl_add_u64 v[86:87], s[48:49], 0, v[4:5]
	v_mul_u32_u24_e32 v186, 0x7e0, v8
	v_lshl_add_u32 v186, v136, 4, v186
	v_mov_b32_e32 v187, 0
	v_lshl_add_u64 v[188:189], v[86:87], 0, v[186:187]
	global_load_dwordx4 v[146:149], v[188:189], off
	v_lshlrev_b32_e32 v186, 4, v136
	v_lshlrev_b32_e32 v187, 5, v8
	v_sub_u32_e32 v186, v186, v187
	v_ashrrev_i32_e32 v187, 31, v186
	v_lshl_add_u64 v[188:189], v[76:77], 0, v[186:187]
	global_load_dwordx4 v[150:153], v[188:189], off
	s_mov_b64 s[42:43], 0x1000
	v_cndmask_b32_e64 v4, 0, v6, s[50:51]
	v_lshl_add_u64 v[36:37], v[86:87], 0, s[42:43]
	s_mov_b64 s[42:43], 0x1800
	v_lshl_add_u64 v[80:81], v[78:79], 1, s[8:9]
	v_add_u32_e32 v79, s27, v4
	v_lshl_add_u64 v[82:83], v[86:87], 0, s[42:43]
	v_max_i32_e32 v4, -1, v6
	s_or_b32 s80, s27, 1
	v_add_u32_e32 v92, s80, v4
	v_max_i32_e32 v4, -2, v6
	s_or_b32 s81, s27, 2
	v_add_u32_e32 v93, s81, v4
	s_cmp_gt_i32 s46, -1
	v_or_b32_e32 v4, s20, v136
	s_cselect_b64 s[42:43], -1, 0
	v_cndmask_b32_e64 v4, 0, v4, s[42:43]
	v_add_u32_e32 v94, s27, v4
	global_load_dwordx4 v[48:51], v[108:109], off
	global_load_dwordx4 v[44:47], v[110:111], off
	global_load_dwordx4 v[88:91], v[112:113], off
	v_lshl_add_u32 v95, v8, 5, s6
	v_cmp_lt_i32_e64 s[48:49], -2, v6
	v_cmp_lt_i32_e64 s[44:45], -3, v6
	s_nop 0
	v_add_co_u32_e32 v96, vcc, s73, v86
	v_mad_u32_u24 v121, v136, s76, v95
	s_nop 0
	v_addc_co_u32_e32 v97, vcc, 0, v87, vcc
	s_nop 0
	s_nop 0
	v_add_u32_e32 v186, s20, v136
	v_add_u32_e32 v187, -16, v186
	v_max_i32_e32 v187, 0, v187
	v_add_u32_e32 v187, s27, v187
	v_add_u32_e32 v186, s27, v186
	v_mad_i64_i32 v[188:189], s[46:47], v187, s72, v[80:81]
	global_load_dwordx4 v[222:225], v[188:189], off
	global_load_dwordx4 v[242:245], v[188:189], off offset:64
	v_mad_i64_i32 v[188:189], s[46:47], v186, s72, v[80:81]
	global_load_dwordx4 v[226:229], v[188:189], off
	global_load_dwordx4 v[246:249], v[188:189], off offset:64
	v_add_u32_e32 v187, 16, v186
	v_mad_i64_i32 v[188:189], s[46:47], v187, s72, v[80:81]
	global_load_dwordx4 v[230:233], v[188:189], off
	global_load_dwordx4 v[250:253], v[188:189], off offset:64
	v_add_u32_e32 v187, 32, v186
	v_mad_i64_i32 v[188:189], s[46:47], v187, s72, v[80:81]
	global_load_dwordx4 v[234:237], v[188:189], off
	global_load_dwordx4 v[190:193], v[188:189], off offset:64
	v_add_u32_e32 v187, 48, v186
	v_mad_i64_i32 v[188:189], s[46:47], v187, s72, v[80:81]
	global_load_dwordx4 v[238:241], v[188:189], off
	global_load_dwordx4 v[194:197], v[188:189], off offset:64
	v_or_b32_e32 v140, 16, v136
	v_or_b32_e32 v139, 32, v136
	v_or_b32_e32 v137, 48, v136
	v_mov_b64_e32 v[102:103], s[8:9]
	s_waitcnt vmcnt(13)
; __device__ __forceinline__ void ld8bf(const bf16_t* p, float (&o)[8]) { unpack8(*(const u32x4*)p, o); }
; __device__ __forceinline__ bf16x8 pack_frag(const float (&v)[8]) { return __builtin_bit_cast(bf16x8, pack8(v)); }
; __device__ __forceinline__ void w_lru_m1(const Args& a, int l, unsigned char* ws, const bf16_t* proj, bf16_t* y, LAS unsigned char* wl, int b, int ck_, int h, int lane) {
;     ...
;     for (int kk = 0; kk < 2; ++kk) { const int ch0 = 64 * h + 32 * kk + 8 * fq; float w[4][8], bs[8];
; #pragma unroll
;         for (int j = 0; j < 8; ++j) { bs[j] = cbias[ch0 + j];
; #pragma unroll
;             for (int k = 0; k < 4; ++k) w[k][j] = cw[k * 512 + ch0 + j]; }
; #pragma unroll
;         for (int tb = 0; tb < 4; ++tb) { const int tok = 16 * tb + lo, t = 64 * ck_ + tok; float s[8];
; #pragma unroll
;             for (int j = 0; j < 8; ++j) s[j] = bs[j];
; #pragma unroll
;             for (int k = 0; k < 4; ++k) { const int tt = t - 3 + k; float x[8];
;                 ld8bf(proj + (size_t)(b * SEQ + (tt >= 0 ? tt : 0)) * NIN + C_LX + ch0, x);
; #pragma unroll
;                 for (int j = 0; j < 8; ++j) s[j] += (tt >= 0 ? w[k][j] : 0.f) * x[j]; }
;             Xf[tb][kk] = pack_frag(s);
; #pragma unroll
;             for (int j = 0; j < 8; ++j) xcf[tok * 65 + 32 * kk + 8 * fq + j] = s[j]; }
	v_lshl_add_u32 v198, v144, 4, s6
	v_lshl_add_u32 v154, v136, 4, s6
	v_mov_b32_e32 v199, v95
	ds_write_b128 v198, v[146:149] offset:16640
	ds_write_b128 v154, v[150:153] offset:17664
	ds_read_b128 v[32:35], v199 offset:16640
	ds_read_b128 v[24:27], v199 offset:16656
	ds_read_b128 v[40:43], v199 offset:16896
	ds_read_b128 v[28:31], v199 offset:16912
	ds_read_b128 v[68:71], v199 offset:17152
	ds_read_b128 v[36:39], v199 offset:17168
	ds_read_b128 v[104:107], v199 offset:17408
	ds_read_b128 v[114:117], v199 offset:17424
	ds_read_b128 v[4:7], v199 offset:17664
	ds_read_b128 v[20:23], v199 offset:17680
	s_waitcnt vmcnt(0) lgkmcnt(0)
	v_mov_b32_dpp v72, v222 row_ror:3 row_mask:0xf bank_mask:0xf
	v_mov_b32_dpp v73, v223 row_ror:3 row_mask:0xf bank_mask:0xf
	v_mov_b32_dpp v74, v224 row_ror:3 row_mask:0xf bank_mask:0xf
	v_mov_b32_dpp v75, v225 row_ror:3 row_mask:0xf bank_mask:0xf
	v_mov_b32_dpp v72, v226 row_shr:3 row_mask:0xf bank_mask:0xf
	v_mov_b32_dpp v73, v227 row_shr:3 row_mask:0xf bank_mask:0xf
	v_mov_b32_dpp v74, v228 row_shr:3 row_mask:0xf bank_mask:0xf
	v_mov_b32_dpp v75, v229 row_shr:3 row_mask:0xf bank_mask:0xf
	v_mov_b32_dpp v16, v222 row_ror:2 row_mask:0xf bank_mask:0xf
	v_mov_b32_dpp v17, v223 row_ror:2 row_mask:0xf bank_mask:0xf
	v_mov_b32_dpp v18, v224 row_ror:2 row_mask:0xf bank_mask:0xf
	v_mov_b32_dpp v19, v225 row_ror:2 row_mask:0xf bank_mask:0xf
	v_mov_b32_dpp v16, v226 row_shr:2 row_mask:0xf bank_mask:0xf
	v_mov_b32_dpp v17, v227 row_shr:2 row_mask:0xf bank_mask:0xf
	v_mov_b32_dpp v18, v228 row_shr:2 row_mask:0xf bank_mask:0xf
	v_mov_b32_dpp v19, v229 row_shr:2 row_mask:0xf bank_mask:0xf
	v_mov_b32_dpp v12, v222 row_ror:1 row_mask:0xf bank_mask:0xf
	v_mov_b32_dpp v13, v223 row_ror:1 row_mask:0xf bank_mask:0xf
	v_mov_b32_dpp v14, v224 row_ror:1 row_mask:0xf bank_mask:0xf
	v_mov_b32_dpp v15, v225 row_ror:1 row_mask:0xf bank_mask:0xf
	v_mov_b32_dpp v12, v226 row_shr:1 row_mask:0xf bank_mask:0xf
	v_mov_b32_dpp v13, v227 row_shr:1 row_mask:0xf bank_mask:0xf
	v_mov_b32_dpp v14, v228 row_shr:1 row_mask:0xf bank_mask:0xf
	v_mov_b32_dpp v15, v229 row_shr:1 row_mask:0xf bank_mask:0xf
	v_mov_b64_e32 v[8:9], v[226:227]
	v_mov_b64_e32 v[10:11], v[228:229]
	v_lshlrev_b32_e32 v82, 16, v72
	v_lshlrev_b32_e32 v84, 16, v73
	v_and_b32_e32 v83, 0xffff0000, v72
	v_and_b32_e32 v85, 0xffff0000, v73
	v_cndmask_b32_e64 v73, 0, v33, s[50:51]
	v_cndmask_b32_e64 v72, 0, v32, s[50:51]
	v_cndmask_b32_e64 v99, 0, v35, s[50:51]
	v_cndmask_b32_e64 v98, 0, v34, s[50:51]
	v_pk_fma_f32 v[84:85], v[98:99], v[84:85], v[6:7]
	v_pk_fma_f32 v[72:73], v[72:73], v[82:83], v[4:5]
	v_lshlrev_b32_e32 v82, 16, v17
	v_lshlrev_b32_e32 v98, 16, v16
	v_and_b32_e32 v83, 0xffff0000, v17
	v_and_b32_e32 v99, 0xffff0000, v16
	v_cndmask_b32_e64 v17, 0, v43, s[48:49]
	v_cndmask_b32_e64 v16, 0, v42, s[48:49]
	v_cndmask_b32_e64 v119, 0, v41, s[48:49]
	v_cndmask_b32_e64 v118, 0, v40, s[48:49]
	v_pk_fma_f32 v[72:73], v[118:119], v[98:99], v[72:73]
	v_pk_fma_f32 v[16:17], v[16:17], v[82:83], v[84:85]
	v_lshlrev_b32_e32 v82, 16, v12
	v_lshlrev_b32_e32 v84, 16, v13
	v_and_b32_e32 v83, 0xffff0000, v12
	v_and_b32_e32 v85, 0xffff0000, v13
	v_cndmask_b32_e64 v13, 0, v69, s[44:45]
	v_cndmask_b32_e64 v12, 0, v68, s[44:45]
	v_cndmask_b32_e64 v99, 0, v71, s[44:45]
	v_cndmask_b32_e64 v98, 0, v70, s[44:45]
	v_pk_fma_f32 v[16:17], v[98:99], v[84:85], v[16:17]
	v_pk_fma_f32 v[12:13], v[12:13], v[82:83], v[72:73]
	v_lshlrev_b32_e32 v84, 16, v9
	v_lshlrev_b32_e32 v98, 16, v8
	v_and_b32_e32 v85, 0xffff0000, v9
	v_and_b32_e32 v99, 0xffff0000, v8
	v_cndmask_b32_e64 v73, 0, v107, s[42:43]
	v_cndmask_b32_e64 v72, 0, v106, s[42:43]
	v_cndmask_b32_e64 v83, 0, v105, s[42:43]
	v_cndmask_b32_e64 v82, 0, v104, s[42:43]
	v_pk_fma_f32 v[8:9], v[82:83], v[98:99], v[12:13]
	v_pk_fma_f32 v[12:13], v[72:73], v[84:85], v[16:17]
	v_cvt_pk_bf16_f32 v16, v8, v9
	v_cvt_pk_bf16_f32 v17, v12, v13
	ds_write2_b32 v121, v12, v13 offset0:2 offset1:3
	ds_write2_b32 v121, v8, v9 offset1:1
	v_lshlrev_b32_e32 v8, 16, v74
	v_lshlrev_b32_e32 v12, 16, v75
	v_and_b32_e32 v9, 0xffff0000, v74
	v_and_b32_e32 v13, 0xffff0000, v75
	v_cndmask_b32_e64 v75, 0, v25, s[50:51]
	v_cndmask_b32_e64 v74, 0, v24, s[50:51]
	v_cndmask_b32_e64 v85, 0, v27, s[50:51]
	v_cndmask_b32_e64 v84, 0, v26, s[50:51]
	v_pk_fma_f32 v[12:13], v[84:85], v[12:13], v[22:23]
	v_pk_fma_f32 v[8:9], v[74:75], v[8:9], v[20:21]
	v_lshlrev_b32_e32 v74, 16, v19
	v_lshlrev_b32_e32 v84, 16, v18
	v_and_b32_e32 v75, 0xffff0000, v19
	v_and_b32_e32 v85, 0xffff0000, v18
	v_cndmask_b32_e64 v19, 0, v31, s[48:49]
	v_cndmask_b32_e64 v18, 0, v30, s[48:49]
	v_cndmask_b32_e64 v99, 0, v29, s[48:49]
	v_cndmask_b32_e64 v98, 0, v28, s[48:49]
	v_pk_fma_f32 v[8:9], v[98:99], v[84:85], v[8:9]
	v_pk_fma_f32 v[12:13], v[18:19], v[74:75], v[12:13]
	v_lshlrev_b32_e32 v18, 16, v14
	v_lshlrev_b32_e32 v74, 16, v15
	v_and_b32_e32 v19, 0xffff0000, v14
	v_and_b32_e32 v75, 0xffff0000, v15
	v_cndmask_b32_e64 v15, 0, v37, s[44:45]
	v_cndmask_b32_e64 v14, 0, v36, s[44:45]
	v_cndmask_b32_e64 v85, 0, v39, s[44:45]
	v_cndmask_b32_e64 v84, 0, v38, s[44:45]
	v_pk_fma_f32 v[12:13], v[84:85], v[74:75], v[12:13]
	v_pk_fma_f32 v[8:9], v[14:15], v[18:19], v[8:9]
	v_lshlrev_b32_e32 v14, 16, v11
	v_lshlrev_b32_e32 v18, 16, v10
	v_and_b32_e32 v15, 0xffff0000, v11
	v_and_b32_e32 v19, 0xffff0000, v10
	v_cndmask_b32_e64 v75, 0, v117, s[42:43]
	v_cndmask_b32_e64 v74, 0, v116, s[42:43]
	v_cndmask_b32_e64 v85, 0, v115, s[42:43]
	v_cndmask_b32_e64 v84, 0, v114, s[42:43]
	v_add_u32_e32 v98, s40, v140
	v_pk_fma_f32 v[8:9], v[84:85], v[18:19], v[8:9]
	v_pk_fma_f32 v[10:11], v[74:75], v[14:15], v[12:13]
	v_cmp_lt_i32_e64 s[62:63], -1, v98
; __device__ __forceinline__ void ld8bf(const bf16_t* p, float (&o)[8]) { unpack8(*(const u32x4*)p, o); }
; __device__ __forceinline__ bf16x8 pack_frag(const float (&v)[8]) { return __builtin_bit_cast(bf16x8, pack8(v)); }
; __device__ __forceinline__ void w_lru_m1(const Args& a, int l, unsigned char* ws, const bf16_t* proj, bf16_t* y, LAS unsigned char* wl, int b, int ck_, int h, int lane) {
;     ...
;         for (int tb = 0; tb < 4; ++tb) { const int tok = 16 * tb + lo, t = 64 * ck_ + tok; float s[8];
; #pragma unroll
;             for (int j = 0; j < 8; ++j) s[j] = bs[j];
; #pragma unroll
;             for (int k = 0; k < 4; ++k) { const int tt = t - 3 + k; float x[8];
;                 ld8bf(proj + (size_t)(b * SEQ + (tt >= 0 ? tt : 0)) * NIN + C_LX + ch0, x);
; #pragma unroll
;                 for (int j = 0; j < 8; ++j) s[j] += (tt >= 0 ? w[k][j] : 0.f) * x[j]; }
;             Xf[tb][kk] = pack_frag(s);
; #pragma unroll
;             for (int j = 0; j < 8; ++j) xcf[tok * 65 + 32 * kk + 8 * fq + j] = s[j]; }
	v_cvt_pk_bf16_f32 v18, v8, v9
	ds_write2_b32 v121, v10, v11 offset0:6 offset1:7
	ds_write2_b32 v121, v8, v9 offset0:4 offset1:5
	v_cndmask_b32_e64 v8, 0, v98, s[62:63]
	v_cmp_lt_i32_e64 s[60:61], -2, v98
	v_max_i32_e32 v12, -1, v98
	v_cmp_lt_i32_e64 s[58:59], -3, v98
	v_max_i32_e32 v98, -2, v98
	v_add_u32_e32 v142, s81, v98
	v_add_u32_e32 v134, s27, v8
	v_add_u32_e32 v135, s80, v12
	v_mov_b32_dpp v104, v226 row_ror:1 row_mask:0xf bank_mask:0xf
	v_mov_b32_dpp v105, v227 row_ror:1 row_mask:0xf bank_mask:0xf
	v_mov_b32_dpp v106, v228 row_ror:1 row_mask:0xf bank_mask:0xf
	v_mov_b32_dpp v107, v229 row_ror:1 row_mask:0xf bank_mask:0xf
	v_mov_b32_dpp v104, v230 row_shr:1 row_mask:0xf bank_mask:0xf
	v_mov_b32_dpp v105, v231 row_shr:1 row_mask:0xf bank_mask:0xf
	v_mov_b32_dpp v106, v232 row_shr:1 row_mask:0xf bank_mask:0xf
	v_mov_b32_dpp v107, v233 row_shr:1 row_mask:0xf bank_mask:0xf
	v_or_b32_e32 v98, s20, v140
	v_cvt_pk_bf16_f32 v19, v10, v11
	v_mov_b32_dpp v8, v226 row_ror:3 row_mask:0xf bank_mask:0xf
	v_mov_b32_dpp v9, v227 row_ror:3 row_mask:0xf bank_mask:0xf
	v_mov_b32_dpp v10, v228 row_ror:3 row_mask:0xf bank_mask:0xf
	v_mov_b32_dpp v11, v229 row_ror:3 row_mask:0xf bank_mask:0xf
	v_mov_b32_dpp v8, v230 row_shr:3 row_mask:0xf bank_mask:0xf
	v_mov_b32_dpp v9, v231 row_shr:3 row_mask:0xf bank_mask:0xf
	v_mov_b32_dpp v10, v232 row_shr:3 row_mask:0xf bank_mask:0xf
	v_mov_b32_dpp v11, v233 row_shr:3 row_mask:0xf bank_mask:0xf
	v_cndmask_b32_e64 v98, 0, v98, s[42:43]
	v_mov_b32_dpp v12, v226 row_ror:2 row_mask:0xf bank_mask:0xf
	v_mov_b32_dpp v13, v227 row_ror:2 row_mask:0xf bank_mask:0xf
	v_mov_b32_dpp v14, v228 row_ror:2 row_mask:0xf bank_mask:0xf
	v_mov_b32_dpp v15, v229 row_ror:2 row_mask:0xf bank_mask:0xf
	v_mov_b32_dpp v12, v230 row_shr:2 row_mask:0xf bank_mask:0xf
	v_mov_b32_dpp v13, v231 row_shr:2 row_mask:0xf bank_mask:0xf
	v_mov_b32_dpp v14, v232 row_shr:2 row_mask:0xf bank_mask:0xf
	v_mov_b32_dpp v15, v233 row_shr:2 row_mask:0xf bank_mask:0xf
	v_add_u32_e32 v143, s27, v98
	v_mov_b64_e32 v[114:115], v[230:231]
	v_mov_b64_e32 v[116:117], v[232:233]
	v_mov_b32_e32 v98, 0x1040
	v_mad_u32_u24 v123, v136, s76, v98
	v_cndmask_b32_e64 v127, 0, v35, s[62:63]
	v_cndmask_b32_e64 v126, 0, v34, s[62:63]
	v_cndmask_b32_e64 v129, 0, v41, s[60:61]
	v_cndmask_b32_e64 v128, 0, v40, s[60:61]
	v_add_u32_e32 v125, v95, v123
	v_lshlrev_b32_e32 v98, 16, v8
	v_lshlrev_b32_e32 v118, 16, v9
	v_and_b32_e32 v99, 0xffff0000, v8
	v_and_b32_e32 v119, 0xffff0000, v9
	v_cndmask_b32_e64 v9, 0, v33, s[62:63]
	v_cndmask_b32_e64 v8, 0, v32, s[62:63]
	v_pk_fma_f32 v[118:119], v[126:127], v[118:119], v[6:7]
	v_pk_fma_f32 v[8:9], v[8:9], v[98:99], v[4:5]
	v_lshlrev_b32_e32 v98, 16, v13
	v_lshlrev_b32_e32 v126, 16, v12
	v_and_b32_e32 v99, 0xffff0000, v13
	v_and_b32_e32 v127, 0xffff0000, v12
	v_cndmask_b32_e64 v13, 0, v43, s[60:61]
	v_cndmask_b32_e64 v12, 0, v42, s[60:61]
	v_pk_fma_f32 v[8:9], v[128:129], v[126:127], v[8:9]
	v_pk_fma_f32 v[12:13], v[12:13], v[98:99], v[118:119]
	v_lshlrev_b32_e32 v98, 16, v104
	v_lshlrev_b32_e32 v118, 16, v105
	v_and_b32_e32 v99, 0xffff0000, v104
	v_and_b32_e32 v119, 0xffff0000, v105
	v_cndmask_b32_e64 v105, 0, v69, s[58:59]
	v_cndmask_b32_e64 v104, 0, v68, s[58:59]
	v_cndmask_b32_e64 v127, 0, v71, s[58:59]
	v_cndmask_b32_e64 v126, 0, v70, s[58:59]
	v_pk_fma_f32 v[12:13], v[126:127], v[118:119], v[12:13]
	v_pk_fma_f32 v[8:9], v[104:105], v[98:99], v[8:9]
	v_lshlrev_b32_e32 v98, 16, v115
	v_lshlrev_b32_e32 v104, 16, v114
	v_and_b32_e32 v99, 0xffff0000, v115
	v_and_b32_e32 v105, 0xffff0000, v114
	v_pk_fma_f32 v[8:9], v[82:83], v[104:105], v[8:9]
	v_pk_fma_f32 v[98:99], v[72:73], v[98:99], v[12:13]
	v_cvt_pk_bf16_f32 v12, v8, v9
	v_cvt_pk_bf16_f32 v13, v98, v99
	ds_write2_b32 v125, v98, v99 offset0:2 offset1:3
	ds_write2_b32 v125, v8, v9 offset1:1
	v_lshlrev_b32_e32 v8, 16, v10
	v_lshlrev_b32_e32 v98, 16, v11
	v_and_b32_e32 v9, 0xffff0000, v10
	v_and_b32_e32 v99, 0xffff0000, v11
	v_cndmask_b32_e64 v11, 0, v25, s[62:63]
	v_cndmask_b32_e64 v10, 0, v24, s[62:63]
	v_cndmask_b32_e64 v105, 0, v27, s[62:63]
	v_cndmask_b32_e64 v104, 0, v26, s[62:63]
	v_pk_fma_f32 v[98:99], v[104:105], v[98:99], v[22:23]
	v_pk_fma_f32 v[8:9], v[10:11], v[8:9], v[20:21]
	v_lshlrev_b32_e32 v10, 16, v15
	v_lshlrev_b32_e32 v104, 16, v14
	v_and_b32_e32 v11, 0xffff0000, v15
	v_and_b32_e32 v105, 0xffff0000, v14
	v_cndmask_b32_e64 v15, 0, v31, s[60:61]
	v_cndmask_b32_e64 v14, 0, v30, s[60:61]
	v_cndmask_b32_e64 v115, 0, v29, s[60:61]
	v_cndmask_b32_e64 v114, 0, v28, s[60:61]
	v_pk_fma_f32 v[8:9], v[114:115], v[104:105], v[8:9]
	v_pk_fma_f32 v[10:11], v[14:15], v[10:11], v[98:99]
	v_lshlrev_b32_e32 v14, 16, v106
	v_lshlrev_b32_e32 v98, 16, v107
	v_and_b32_e32 v15, 0xffff0000, v106
	v_and_b32_e32 v99, 0xffff0000, v107
	v_cndmask_b32_e64 v105, 0, v37, s[58:59]
	v_cndmask_b32_e64 v104, 0, v36, s[58:59]
	v_cndmask_b32_e64 v107, 0, v39, s[58:59]
	v_cndmask_b32_e64 v106, 0, v38, s[58:59]
	v_pk_fma_f32 v[10:11], v[106:107], v[98:99], v[10:11]
	v_pk_fma_f32 v[8:9], v[104:105], v[14:15], v[8:9]
	v_lshlrev_b32_e32 v14, 16, v117
	v_lshlrev_b32_e32 v98, 16, v116
	v_and_b32_e32 v15, 0xffff0000, v117
	v_and_b32_e32 v99, 0xffff0000, v116
	v_add_u32_e32 v114, s40, v139
	v_pk_fma_f32 v[8:9], v[84:85], v[98:99], v[8:9]
	v_pk_fma_f32 v[10:11], v[74:75], v[14:15], v[10:11]
	v_cmp_lt_i32_e64 s[56:57], -1, v114
	v_cvt_pk_bf16_f32 v14, v8, v9
	ds_write2_b32 v125, v10, v11 offset0:6 offset1:7
	ds_write2_b32 v125, v8, v9 offset0:4 offset1:5
	v_cndmask_b32_e64 v8, 0, v114, s[56:57]
	v_max_i32_e32 v98, -1, v114
	v_add_u32_e32 v130, s27, v8
	v_add_u32_e32 v131, s80, v98
	v_cvt_pk_bf16_f32 v15, v10, v11
; __device__ __forceinline__ void ld8bf(const bf16_t* p, float (&o)[8]) { unpack8(*(const u32x4*)p, o); }
; __device__ __forceinline__ bf16x8 pack_frag(const float (&v)[8]) { return __builtin_bit_cast(bf16x8, pack8(v)); }
; __device__ __forceinline__ void w_lru_m1(const Args& a, int l, unsigned char* ws, const bf16_t* proj, bf16_t* y, LAS unsigned char* wl, int b, int ck_, int h, int lane) {
;     ...
;         for (int tb = 0; tb < 4; ++tb) { const int tok = 16 * tb + lo, t = 64 * ck_ + tok; float s[8];
; #pragma unroll
;             for (int j = 0; j < 8; ++j) s[j] = bs[j];
; #pragma unroll
;             for (int k = 0; k < 4; ++k) { const int tt = t - 3 + k; float x[8];
;                 ld8bf(proj + (size_t)(b * SEQ + (tt >= 0 ? tt : 0)) * NIN + C_LX + ch0, x);
; #pragma unroll
;                 for (int j = 0; j < 8; ++j) s[j] += (tt >= 0 ? w[k][j] : 0.f) * x[j]; }
;             Xf[tb][kk] = pack_frag(s);
; #pragma unroll
;             for (int j = 0; j < 8; ++j) xcf[tok * 65 + 32 * kk + 8 * fq + j] = s[j]; }
	v_mov_b32_dpp v8, v230 row_ror:3 row_mask:0xf bank_mask:0xf
	v_mov_b32_dpp v9, v231 row_ror:3 row_mask:0xf bank_mask:0xf
	v_mov_b32_dpp v10, v232 row_ror:3 row_mask:0xf bank_mask:0xf
	v_mov_b32_dpp v11, v233 row_ror:3 row_mask:0xf bank_mask:0xf
	v_mov_b32_dpp v8, v234 row_shr:3 row_mask:0xf bank_mask:0xf
	v_mov_b32_dpp v9, v235 row_shr:3 row_mask:0xf bank_mask:0xf
	v_mov_b32_dpp v10, v236 row_shr:3 row_mask:0xf bank_mask:0xf
	v_mov_b32_dpp v11, v237 row_shr:3 row_mask:0xf bank_mask:0xf
	v_cmp_lt_i32_e64 s[54:55], -2, v114
	v_mov_b32_dpp v104, v230 row_ror:2 row_mask:0xf bank_mask:0xf
	v_mov_b32_dpp v105, v231 row_ror:2 row_mask:0xf bank_mask:0xf
	v_mov_b32_dpp v106, v232 row_ror:2 row_mask:0xf bank_mask:0xf
	v_mov_b32_dpp v107, v233 row_ror:2 row_mask:0xf bank_mask:0xf
	v_mov_b32_dpp v104, v234 row_shr:2 row_mask:0xf bank_mask:0xf
	v_mov_b32_dpp v105, v235 row_shr:2 row_mask:0xf bank_mask:0xf
	v_mov_b32_dpp v106, v236 row_shr:2 row_mask:0xf bank_mask:0xf
	v_mov_b32_dpp v107, v237 row_shr:2 row_mask:0xf bank_mask:0xf
	v_max_i32_e32 v98, -2, v114
	v_add_u32_e32 v132, s81, v98
	v_cmp_lt_i32_e64 s[52:53], -3, v114
	v_mov_b32_dpp v114, v230 row_ror:1 row_mask:0xf bank_mask:0xf
	v_mov_b32_dpp v115, v231 row_ror:1 row_mask:0xf bank_mask:0xf
	v_mov_b32_dpp v116, v232 row_ror:1 row_mask:0xf bank_mask:0xf
	v_mov_b32_dpp v117, v233 row_ror:1 row_mask:0xf bank_mask:0xf
	v_mov_b32_dpp v114, v234 row_shr:1 row_mask:0xf bank_mask:0xf
	v_mov_b32_dpp v115, v235 row_shr:1 row_mask:0xf bank_mask:0xf
	v_mov_b32_dpp v116, v236 row_shr:1 row_mask:0xf bank_mask:0xf
	v_mov_b32_dpp v117, v237 row_shr:1 row_mask:0xf bank_mask:0xf
	v_or_b32_e32 v98, s20, v139
	v_cndmask_b32_e64 v98, 0, v98, s[42:43]
	v_add_u32_e32 v133, s27, v98
	v_mov_b64_e32 v[126:127], v[234:235]
	v_mov_b64_e32 v[128:129], v[236:237]
	v_mov_b32_e32 v98, 0x2080
	v_mad_u32_u24 v141, v136, s76, v98
	v_cndmask_b32_e64 v147, 0, v35, s[56:57]
	v_cndmask_b32_e64 v146, 0, v34, s[56:57]
	v_cndmask_b32_e64 v149, 0, v41, s[54:55]
	v_cndmask_b32_e64 v148, 0, v40, s[54:55]
	v_add_u32_e32 v124, v95, v141
	v_lshlrev_b32_e32 v98, 16, v8
	v_lshlrev_b32_e32 v118, 16, v9
	v_and_b32_e32 v99, 0xffff0000, v8
	v_and_b32_e32 v119, 0xffff0000, v9
	v_cndmask_b32_e64 v9, 0, v33, s[56:57]
	v_cndmask_b32_e64 v8, 0, v32, s[56:57]
	v_pk_fma_f32 v[118:119], v[146:147], v[118:119], v[6:7]
	v_pk_fma_f32 v[8:9], v[8:9], v[98:99], v[4:5]
	v_lshlrev_b32_e32 v98, 16, v105
	v_lshlrev_b32_e32 v146, 16, v104
	v_and_b32_e32 v99, 0xffff0000, v105
	v_and_b32_e32 v147, 0xffff0000, v104
	v_cndmask_b32_e64 v105, 0, v43, s[54:55]
	v_cndmask_b32_e64 v104, 0, v42, s[54:55]
	v_pk_fma_f32 v[8:9], v[148:149], v[146:147], v[8:9]
	v_pk_fma_f32 v[98:99], v[104:105], v[98:99], v[118:119]
	v_lshlrev_b32_e32 v104, 16, v114
	v_lshlrev_b32_e32 v118, 16, v115
	v_and_b32_e32 v105, 0xffff0000, v114
	v_and_b32_e32 v119, 0xffff0000, v115
	v_cndmask_b32_e64 v115, 0, v69, s[52:53]
	v_cndmask_b32_e64 v114, 0, v68, s[52:53]
	v_cndmask_b32_e64 v147, 0, v71, s[52:53]
	v_cndmask_b32_e64 v146, 0, v70, s[52:53]
	v_pk_fma_f32 v[98:99], v[146:147], v[118:119], v[98:99]
	v_pk_fma_f32 v[8:9], v[114:115], v[104:105], v[8:9]
	v_lshlrev_b32_e32 v104, 16, v127
	v_lshlrev_b32_e32 v114, 16, v126
	v_and_b32_e32 v105, 0xffff0000, v127
	v_and_b32_e32 v115, 0xffff0000, v126
	v_pk_fma_f32 v[114:115], v[82:83], v[114:115], v[8:9]
	v_pk_fma_f32 v[98:99], v[72:73], v[104:105], v[98:99]
	v_cvt_pk_bf16_f32 v8, v114, v115
	v_cvt_pk_bf16_f32 v9, v98, v99
	ds_write2_b32 v124, v98, v99 offset0:2 offset1:3
	ds_write2_b32 v124, v114, v115 offset1:1
	v_lshlrev_b32_e32 v98, 16, v10
	v_lshlrev_b32_e32 v104, 16, v11
	v_and_b32_e32 v99, 0xffff0000, v10
	v_and_b32_e32 v105, 0xffff0000, v11
	v_cndmask_b32_e64 v11, 0, v25, s[56:57]
	v_cndmask_b32_e64 v10, 0, v24, s[56:57]
	v_cndmask_b32_e64 v115, 0, v27, s[56:57]
	v_cndmask_b32_e64 v114, 0, v26, s[56:57]
	v_pk_fma_f32 v[104:105], v[114:115], v[104:105], v[22:23]
	v_pk_fma_f32 v[10:11], v[10:11], v[98:99], v[20:21]
	v_lshlrev_b32_e32 v98, 16, v107
	v_lshlrev_b32_e32 v114, 16, v106
	v_and_b32_e32 v99, 0xffff0000, v107
	v_and_b32_e32 v115, 0xffff0000, v106
	v_cndmask_b32_e64 v107, 0, v31, s[54:55]
	v_cndmask_b32_e64 v106, 0, v30, s[54:55]
	v_cndmask_b32_e64 v119, 0, v29, s[54:55]
	v_cndmask_b32_e64 v118, 0, v28, s[54:55]
	v_pk_fma_f32 v[10:11], v[118:119], v[114:115], v[10:11]
	v_pk_fma_f32 v[98:99], v[106:107], v[98:99], v[104:105]
	v_lshlrev_b32_e32 v104, 16, v116
	v_lshlrev_b32_e32 v106, 16, v117
	v_and_b32_e32 v105, 0xffff0000, v116
	v_and_b32_e32 v107, 0xffff0000, v117
	v_cndmask_b32_e64 v115, 0, v37, s[52:53]
	v_cndmask_b32_e64 v114, 0, v36, s[52:53]
	v_cndmask_b32_e64 v117, 0, v39, s[52:53]
	v_cndmask_b32_e64 v116, 0, v38, s[52:53]
	v_pk_fma_f32 v[98:99], v[116:117], v[106:107], v[98:99]
	v_pk_fma_f32 v[10:11], v[114:115], v[104:105], v[10:11]
	v_lshlrev_b32_e32 v104, 16, v129
	v_and_b32_e32 v105, 0xffff0000, v129
	v_add_u32_e32 v118, s40, v137
	v_lshlrev_b32_e32 v106, 16, v128
	v_and_b32_e32 v107, 0xffff0000, v128
	v_pk_fma_f32 v[98:99], v[74:75], v[104:105], v[98:99]
	v_cmp_lt_i32_e64 s[46:47], -1, v118
	v_pk_fma_f32 v[106:107], v[84:85], v[106:107], v[10:11]
	v_cvt_pk_bf16_f32 v11, v98, v99
	ds_write2_b32 v124, v98, v99 offset0:6 offset1:7
	ds_write2_b32 v124, v106, v107 offset0:4 offset1:5
	v_cndmask_b32_e64 v98, 0, v118, s[46:47]
	v_add_u32_e32 v126, s27, v98
	v_cvt_pk_bf16_f32 v10, v106, v107
	v_mov_b32_dpp v104, v234 row_ror:3 row_mask:0xf bank_mask:0xf
	v_mov_b32_dpp v105, v235 row_ror:3 row_mask:0xf bank_mask:0xf
	v_mov_b32_dpp v106, v236 row_ror:3 row_mask:0xf bank_mask:0xf
	v_mov_b32_dpp v107, v237 row_ror:3 row_mask:0xf bank_mask:0xf
; __device__ __forceinline__ void ld8bf(const bf16_t* p, float (&o)[8]) { unpack8(*(const u32x4*)p, o); }
; __device__ __forceinline__ bf16x8 pack_frag(const float (&v)[8]) { return __builtin_bit_cast(bf16x8, pack8(v)); }
; __device__ __forceinline__ void w_lru_m1(const Args& a, int l, unsigned char* ws, const bf16_t* proj, bf16_t* y, LAS unsigned char* wl, int b, int ck_, int h, int lane) {
;     ...
;         for (int tb = 0; tb < 4; ++tb) { const int tok = 16 * tb + lo, t = 64 * ck_ + tok; float s[8];
; #pragma unroll
;             for (int j = 0; j < 8; ++j) s[j] = bs[j];
; #pragma unroll
;             for (int k = 0; k < 4; ++k) { const int tt = t - 3 + k; float x[8];
;                 ld8bf(proj + (size_t)(b * SEQ + (tt >= 0 ? tt : 0)) * NIN + C_LX + ch0, x);
; #pragma unroll
;                 for (int j = 0; j < 8; ++j) s[j] += (tt >= 0 ? w[k][j] : 0.f) * x[j]; }
;             Xf[tb][kk] = pack_frag(s);
; #pragma unroll
;             for (int j = 0; j < 8; ++j) xcf[tok * 65 + 32 * kk + 8 * fq + j] = s[j]; }
	v_mov_b32_dpp v104, v238 row_shr:3 row_mask:0xf bank_mask:0xf
	v_mov_b32_dpp v105, v239 row_shr:3 row_mask:0xf bank_mask:0xf
	v_mov_b32_dpp v106, v240 row_shr:3 row_mask:0xf bank_mask:0xf
	v_mov_b32_dpp v107, v241 row_shr:3 row_mask:0xf bank_mask:0xf
	v_max_i32_e32 v98, -1, v118
	v_add_u32_e32 v127, s80, v98
	v_mov_b32_dpp v114, v234 row_ror:2 row_mask:0xf bank_mask:0xf
	v_mov_b32_dpp v115, v235 row_ror:2 row_mask:0xf bank_mask:0xf
	v_mov_b32_dpp v116, v236 row_ror:2 row_mask:0xf bank_mask:0xf
	v_mov_b32_dpp v117, v237 row_ror:2 row_mask:0xf bank_mask:0xf
	v_mov_b32_dpp v114, v238 row_shr:2 row_mask:0xf bank_mask:0xf
	v_mov_b32_dpp v115, v239 row_shr:2 row_mask:0xf bank_mask:0xf
	v_mov_b32_dpp v116, v240 row_shr:2 row_mask:0xf bank_mask:0xf
	v_mov_b32_dpp v117, v241 row_shr:2 row_mask:0xf bank_mask:0xf
	v_max_i32_e32 v98, -2, v118
	v_add_u32_e32 v128, s81, v98
	v_mov_b32_dpp v146, v234 row_ror:1 row_mask:0xf bank_mask:0xf
	v_mov_b32_dpp v147, v235 row_ror:1 row_mask:0xf bank_mask:0xf
	v_mov_b32_dpp v148, v236 row_ror:1 row_mask:0xf bank_mask:0xf
	v_mov_b32_dpp v149, v237 row_ror:1 row_mask:0xf bank_mask:0xf
	v_mov_b32_dpp v146, v238 row_shr:1 row_mask:0xf bank_mask:0xf
	v_mov_b32_dpp v147, v239 row_shr:1 row_mask:0xf bank_mask:0xf
	v_mov_b32_dpp v148, v240 row_shr:1 row_mask:0xf bank_mask:0xf
	v_mov_b32_dpp v149, v241 row_shr:1 row_mask:0xf bank_mask:0xf
	v_or_b32_e32 v98, s20, v137
	v_cndmask_b32_e64 v98, 0, v98, s[42:43]
	v_add_u32_e32 v129, s27, v98
	v_mov_b64_e32 v[150:151], v[238:239]
	v_mov_b64_e32 v[152:153], v[240:241]
	v_mov_b32_e32 v80, 0x30c0
	v_cmp_lt_i32_e64 s[40:41], -2, v118
	v_mad_u32_u24 v138, v136, s76, v80
	v_cndmask_b32_e64 v33, 0, v33, s[46:47]
	v_cndmask_b32_e64 v32, 0, v32, s[46:47]
	v_cndmask_b32_e64 v35, 0, v35, s[46:47]
	v_cndmask_b32_e64 v34, 0, v34, s[46:47]
	v_cmp_lt_i32_e32 vcc, -3, v118
	v_cndmask_b32_e64 v43, 0, v43, s[40:41]
	v_cndmask_b32_e64 v42, 0, v42, s[40:41]
	v_cndmask_b32_e64 v41, 0, v41, s[40:41]
	v_cndmask_b32_e64 v40, 0, v40, s[40:41]
	v_add_u32_e32 v120, v95, v138
	v_cndmask_b32_e64 v25, 0, v25, s[46:47]
	v_cndmask_b32_e64 v24, 0, v24, s[46:47]
	v_cndmask_b32_e64 v27, 0, v27, s[46:47]
	v_cndmask_b32_e64 v26, 0, v26, s[46:47]
	v_cndmask_b32_e64 v29, 0, v29, s[40:41]
	v_cndmask_b32_e64 v28, 0, v28, s[40:41]
	s_mov_b64 s[80:81], 0x1080
	v_lshlrev_b32_e32 v80, 16, v104
	v_lshlrev_b32_e32 v98, 16, v105
	v_and_b32_e32 v81, 0xffff0000, v104
	v_and_b32_e32 v99, 0xffff0000, v105
	v_pk_fma_f32 v[6:7], v[34:35], v[98:99], v[6:7]
	v_pk_fma_f32 v[4:5], v[32:33], v[80:81], v[4:5]
	v_lshlrev_b32_e32 v32, 16, v115
	v_lshlrev_b32_e32 v34, 16, v114
	v_and_b32_e32 v33, 0xffff0000, v115
	v_and_b32_e32 v35, 0xffff0000, v114
	v_pk_fma_f32 v[4:5], v[40:41], v[34:35], v[4:5]
	v_pk_fma_f32 v[6:7], v[42:43], v[32:33], v[6:7]
	v_lshlrev_b32_e32 v32, 16, v146
	v_lshlrev_b32_e32 v34, 16, v147
	v_and_b32_e32 v33, 0xffff0000, v146
	v_and_b32_e32 v35, 0xffff0000, v147
	v_cndmask_b32_e32 v41, 0, v69, vcc
	v_cndmask_b32_e32 v40, 0, v68, vcc
	v_cndmask_b32_e32 v43, 0, v71, vcc
	v_cndmask_b32_e32 v42, 0, v70, vcc
	v_pk_fma_f32 v[6:7], v[42:43], v[34:35], v[6:7]
	v_pk_fma_f32 v[4:5], v[40:41], v[32:33], v[4:5]
	v_lshlrev_b32_e32 v32, 16, v151
	v_and_b32_e32 v33, 0xffff0000, v151
	v_lshlrev_b32_e32 v34, 16, v150
	v_and_b32_e32 v35, 0xffff0000, v150
	v_pk_fma_f32 v[6:7], v[72:73], v[32:33], v[6:7]
	v_pk_fma_f32 v[34:35], v[82:83], v[34:35], v[4:5]
	v_cvt_pk_bf16_f32 v5, v6, v7
	ds_write2_b32 v120, v6, v7 offset0:2 offset1:3
	ds_write2_b32 v120, v34, v35 offset1:1
	v_lshlrev_b32_e32 v6, 16, v106
	v_lshlrev_b32_e32 v32, 16, v107
	v_and_b32_e32 v7, 0xffff0000, v106
	v_and_b32_e32 v33, 0xffff0000, v107
	v_pk_fma_f32 v[22:23], v[26:27], v[32:33], v[22:23]
	v_pk_fma_f32 v[6:7], v[24:25], v[6:7], v[20:21]
	v_lshlrev_b32_e32 v20, 16, v117
	v_lshlrev_b32_e32 v24, 16, v116
	v_and_b32_e32 v21, 0xffff0000, v117
	v_and_b32_e32 v25, 0xffff0000, v116
	v_cndmask_b32_e64 v27, 0, v31, s[40:41]
	v_cndmask_b32_e64 v26, 0, v30, s[40:41]
	v_pk_fma_f32 v[6:7], v[28:29], v[24:25], v[6:7]
	v_pk_fma_f32 v[20:21], v[26:27], v[20:21], v[22:23]
	v_lshlrev_b32_e32 v22, 16, v148
	v_lshlrev_b32_e32 v24, 16, v149
	v_and_b32_e32 v23, 0xffff0000, v148
	v_and_b32_e32 v25, 0xffff0000, v149
	v_cndmask_b32_e32 v27, 0, v37, vcc
	v_cndmask_b32_e32 v26, 0, v36, vcc
	v_cndmask_b32_e32 v29, 0, v39, vcc
	v_cndmask_b32_e32 v28, 0, v38, vcc
	v_pk_fma_f32 v[20:21], v[28:29], v[24:25], v[20:21]
	v_pk_fma_f32 v[6:7], v[26:27], v[22:23], v[6:7]
	v_lshlrev_b32_e32 v22, 16, v153
	v_and_b32_e32 v23, 0xffff0000, v153
	v_lshlrev_b32_e32 v24, 16, v152
	v_and_b32_e32 v25, 0xffff0000, v152
	v_pk_fma_f32 v[20:21], v[74:75], v[22:23], v[20:21]
	v_pk_fma_f32 v[24:25], v[84:85], v[24:25], v[6:7]
	v_cvt_pk_bf16_f32 v7, v20, v21
	ds_write2_b32 v120, v20, v21 offset0:6 offset1:7
	ds_write2_b32 v120, v24, v25 offset0:4 offset1:5
	v_add_u32_e32 v20, 32, v78
	v_ashrrev_i32_e32 v21, 31, v20
	v_lshl_add_u64 v[84:85], v[86:87], 0, s[80:81]
	s_mov_b64 s[80:81], 0x1880
	v_lshl_add_u64 v[106:107], v[86:87], 0, s[80:81]
	v_lshlrev_b64 v[104:105], 1, v[20:21]
	v_mov_b32_dpp v80, v242 row_ror:3 row_mask:0xf bank_mask:0xf
	v_mov_b32_dpp v81, v243 row_ror:3 row_mask:0xf bank_mask:0xf
	v_mov_b32_dpp v82, v244 row_ror:3 row_mask:0xf bank_mask:0xf
	v_mov_b32_dpp v83, v245 row_ror:3 row_mask:0xf bank_mask:0xf
	v_mov_b32_dpp v80, v246 row_shr:3 row_mask:0xf bank_mask:0xf
	v_mov_b32_dpp v81, v247 row_shr:3 row_mask:0xf bank_mask:0xf
	v_mov_b32_dpp v82, v248 row_shr:3 row_mask:0xf bank_mask:0xf
	v_mov_b32_dpp v83, v249 row_shr:3 row_mask:0xf bank_mask:0xf
	v_cvt_pk_bf16_f32 v4, v34, v35
; __device__ __forceinline__ void ld8bf(const bf16_t* p, float (&o)[8]) { unpack8(*(const u32x4*)p, o); }
; __device__ __forceinline__ bf16x8 pack_frag(const float (&v)[8]) { return __builtin_bit_cast(bf16x8, pack8(v)); }
; __device__ __forceinline__ void w_lru_m1(const Args& a, int l, unsigned char* ws, const bf16_t* proj, bf16_t* y, LAS unsigned char* wl, int b, int ck_, int h, int lane) {
;     ...
;         for (int tb = 0; tb < 4; ++tb) { const int tok = 16 * tb + lo, t = 64 * ck_ + tok; float s[8];
; #pragma unroll
;             for (int j = 0; j < 8; ++j) s[j] = bs[j];
; #pragma unroll
;             for (int k = 0; k < 4; ++k) { const int tt = t - 3 + k; float x[8];
;                 ld8bf(proj + (size_t)(b * SEQ + (tt >= 0 ? tt : 0)) * NIN + C_LX + ch0, x);
; #pragma unroll
;                 for (int j = 0; j < 8; ++j) s[j] += (tt >= 0 ? w[k][j] : 0.f) * x[j]; }
;             Xf[tb][kk] = pack_frag(s);
; #pragma unroll
;             for (int j = 0; j < 8; ++j) xcf[tok * 65 + 32 * kk + 8 * fq + j] = s[j]; }
	v_mov_b32_dpp v32, v242 row_ror:2 row_mask:0xf bank_mask:0xf
	v_mov_b32_dpp v33, v243 row_ror:2 row_mask:0xf bank_mask:0xf
	v_mov_b32_dpp v34, v244 row_ror:2 row_mask:0xf bank_mask:0xf
	v_mov_b32_dpp v35, v245 row_ror:2 row_mask:0xf bank_mask:0xf
	v_mov_b32_dpp v32, v246 row_shr:2 row_mask:0xf bank_mask:0xf
	v_mov_b32_dpp v33, v247 row_shr:2 row_mask:0xf bank_mask:0xf
	v_mov_b32_dpp v34, v248 row_shr:2 row_mask:0xf bank_mask:0xf
	v_mov_b32_dpp v35, v249 row_shr:2 row_mask:0xf bank_mask:0xf
	v_mov_b32_dpp v28, v242 row_ror:1 row_mask:0xf bank_mask:0xf
	v_mov_b32_dpp v29, v243 row_ror:1 row_mask:0xf bank_mask:0xf
	v_mov_b32_dpp v30, v244 row_ror:1 row_mask:0xf bank_mask:0xf
	v_mov_b32_dpp v31, v245 row_ror:1 row_mask:0xf bank_mask:0xf
	v_mov_b32_dpp v28, v246 row_shr:1 row_mask:0xf bank_mask:0xf
	v_mov_b32_dpp v29, v247 row_shr:1 row_mask:0xf bank_mask:0xf
	v_mov_b32_dpp v30, v248 row_shr:1 row_mask:0xf bank_mask:0xf
	v_mov_b32_dpp v31, v249 row_shr:1 row_mask:0xf bank_mask:0xf
	v_cvt_pk_bf16_f32 v6, v24, v25
	v_mov_b64_e32 v[24:25], v[246:247]
	v_mov_b64_e32 v[26:27], v[248:249]
	ds_read_b128 v[40:43], v199 offset:17808
	ds_read_b128 v[72:75], v199 offset:17792
	ds_read_b128 v[68:71], v199 offset:16784
	s_nop 0
	ds_read_b128 v[76:79], v199 offset:16768
	ds_read_b128 v[36:39], v199 offset:17040
	ds_read_b128 v[20:23], v199 offset:17024
	ds_read_b128 v[92:95], v199 offset:17280
	s_nop 0
	ds_read_b128 v[84:87], v199 offset:17296
	s_nop 0
	ds_read_b128 v[96:99], v199 offset:17536
	s_nop 0
	ds_read_b128 v[146:149], v199 offset:17552
	s_waitcnt vmcnt(0) lgkmcnt(0)
	v_lshlrev_b32_e32 v106, 16, v80
	v_lshlrev_b32_e32 v114, 16, v81
	v_and_b32_e32 v107, 0xffff0000, v80
	v_and_b32_e32 v115, 0xffff0000, v81
	v_cndmask_b32_e64 v81, 0, v77, s[50:51]
	v_cndmask_b32_e64 v80, 0, v76, s[50:51]
	v_cndmask_b32_e64 v117, 0, v79, s[50:51]
	v_cndmask_b32_e64 v116, 0, v78, s[50:51]
	v_pk_fma_f32 v[114:115], v[116:117], v[114:115], v[74:75]
	v_pk_fma_f32 v[80:81], v[80:81], v[106:107], v[72:73]
	v_lshlrev_b32_e32 v106, 16, v33
	v_lshlrev_b32_e32 v116, 16, v32
	v_and_b32_e32 v107, 0xffff0000, v33
	v_and_b32_e32 v117, 0xffff0000, v32
	v_cndmask_b32_e64 v33, 0, v23, s[48:49]
	v_cndmask_b32_e64 v32, 0, v22, s[48:49]
	v_cndmask_b32_e64 v119, 0, v21, s[48:49]
	v_cndmask_b32_e64 v118, 0, v20, s[48:49]
	v_pk_fma_f32 v[80:81], v[118:119], v[116:117], v[80:81]
	v_pk_fma_f32 v[32:33], v[32:33], v[106:107], v[114:115]
	v_lshlrev_b32_e32 v106, 16, v28
	v_lshlrev_b32_e32 v114, 16, v29
	v_and_b32_e32 v107, 0xffff0000, v28
	v_and_b32_e32 v115, 0xffff0000, v29
	v_cndmask_b32_e64 v29, 0, v93, s[44:45]
	v_cndmask_b32_e64 v28, 0, v92, s[44:45]
	v_cndmask_b32_e64 v117, 0, v95, s[44:45]
	v_cndmask_b32_e64 v116, 0, v94, s[44:45]
	v_pk_fma_f32 v[32:33], v[116:117], v[114:115], v[32:33]
	v_pk_fma_f32 v[28:29], v[28:29], v[106:107], v[80:81]
	v_lshlrev_b32_e32 v80, 16, v25
	v_lshlrev_b32_e32 v116, 16, v24
	v_and_b32_e32 v81, 0xffff0000, v25
	v_and_b32_e32 v117, 0xffff0000, v24
	v_cndmask_b32_e64 v107, 0, v99, s[42:43]
	v_cndmask_b32_e64 v106, 0, v98, s[42:43]
	v_cndmask_b32_e64 v115, 0, v97, s[42:43]
	v_cndmask_b32_e64 v114, 0, v96, s[42:43]
	v_pk_fma_f32 v[24:25], v[114:115], v[116:117], v[28:29]
	v_pk_fma_f32 v[28:29], v[106:107], v[80:81], v[32:33]
	v_cvt_pk_bf16_f32 v32, v24, v25
	v_cvt_pk_bf16_f32 v33, v28, v29
	ds_write2_b32 v121, v28, v29 offset0:34 offset1:35
	ds_write2_b32 v121, v24, v25 offset0:32 offset1:33
	v_lshlrev_b32_e32 v24, 16, v82
	v_lshlrev_b32_e32 v28, 16, v83
	v_and_b32_e32 v25, 0xffff0000, v82
	v_and_b32_e32 v29, 0xffff0000, v83
	v_cndmask_b32_e64 v81, 0, v69, s[50:51]
	v_cndmask_b32_e64 v80, 0, v68, s[50:51]
	v_cndmask_b32_e64 v83, 0, v71, s[50:51]
	v_cndmask_b32_e64 v82, 0, v70, s[50:51]
	v_pk_fma_f32 v[28:29], v[82:83], v[28:29], v[42:43]
	v_pk_fma_f32 v[24:25], v[80:81], v[24:25], v[40:41]
	v_lshlrev_b32_e32 v80, 16, v35
	v_lshlrev_b32_e32 v82, 16, v34
	v_and_b32_e32 v81, 0xffff0000, v35
	v_and_b32_e32 v83, 0xffff0000, v34
	v_cndmask_b32_e64 v35, 0, v39, s[48:49]
	v_cndmask_b32_e64 v34, 0, v38, s[48:49]
	v_cndmask_b32_e64 v97, 0, v37, s[48:49]
	v_cndmask_b32_e64 v96, 0, v36, s[48:49]
	v_pk_fma_f32 v[24:25], v[96:97], v[82:83], v[24:25]
	v_pk_fma_f32 v[28:29], v[34:35], v[80:81], v[28:29]
	v_lshlrev_b32_e32 v34, 16, v30
	v_lshlrev_b32_e32 v80, 16, v31
	v_and_b32_e32 v35, 0xffff0000, v30
	v_and_b32_e32 v81, 0xffff0000, v31
	v_cndmask_b32_e64 v31, 0, v85, s[44:45]
	v_cndmask_b32_e64 v30, 0, v84, s[44:45]
	v_cndmask_b32_e64 v83, 0, v87, s[44:45]
	v_cndmask_b32_e64 v82, 0, v86, s[44:45]
	v_pk_fma_f32 v[28:29], v[82:83], v[80:81], v[28:29]
	v_pk_fma_f32 v[24:25], v[30:31], v[34:35], v[24:25]
	v_lshlrev_b32_e32 v30, 16, v27
	v_lshlrev_b32_e32 v34, 16, v26
	v_and_b32_e32 v31, 0xffff0000, v27
	v_and_b32_e32 v35, 0xffff0000, v26
	v_cndmask_b32_e64 v117, 0, v149, s[42:43]
	v_cndmask_b32_e64 v116, 0, v148, s[42:43]
	v_cndmask_b32_e64 v119, 0, v147, s[42:43]
	v_cndmask_b32_e64 v118, 0, v146, s[42:43]
	v_pk_fma_f32 v[24:25], v[118:119], v[34:35], v[24:25]
	v_pk_fma_f32 v[26:27], v[116:117], v[30:31], v[28:29]
	v_cvt_pk_bf16_f32 v34, v24, v25
	ds_write2_b32 v121, v26, v27 offset0:38 offset1:39
	ds_write2_b32 v121, v24, v25 offset0:36 offset1:37
	v_cvt_pk_bf16_f32 v35, v26, v27
	v_mov_b32_dpp v24, v246 row_ror:3 row_mask:0xf bank_mask:0xf
	v_mov_b32_dpp v25, v247 row_ror:3 row_mask:0xf bank_mask:0xf
	v_mov_b32_dpp v26, v248 row_ror:3 row_mask:0xf bank_mask:0xf
	v_mov_b32_dpp v27, v249 row_ror:3 row_mask:0xf bank_mask:0xf
	v_mov_b32_dpp v24, v250 row_shr:3 row_mask:0xf bank_mask:0xf
	v_mov_b32_dpp v25, v251 row_shr:3 row_mask:0xf bank_mask:0xf
; __device__ __forceinline__ void ld8bf(const bf16_t* p, float (&o)[8]) { unpack8(*(const u32x4*)p, o); }
; __device__ __forceinline__ bf16x8 pack_frag(const float (&v)[8]) { return __builtin_bit_cast(bf16x8, pack8(v)); }
; __device__ __forceinline__ void w_lru_m1(const Args& a, int l, unsigned char* ws, const bf16_t* proj, bf16_t* y, LAS unsigned char* wl, int b, int ck_, int h, int lane) {
;     ...
;         for (int tb = 0; tb < 4; ++tb) { const int tok = 16 * tb + lo, t = 64 * ck_ + tok; float s[8];
; #pragma unroll
;             for (int j = 0; j < 8; ++j) s[j] = bs[j];
; #pragma unroll
;             for (int k = 0; k < 4; ++k) { const int tt = t - 3 + k; float x[8];
;                 ld8bf(proj + (size_t)(b * SEQ + (tt >= 0 ? tt : 0)) * NIN + C_LX + ch0, x);
; #pragma unroll
;                 for (int j = 0; j < 8; ++j) s[j] += (tt >= 0 ? w[k][j] : 0.f) * x[j]; }
;             Xf[tb][kk] = pack_frag(s);
; #pragma unroll
;             for (int j = 0; j < 8; ++j) xcf[tok * 65 + 32 * kk + 8 * fq + j] = s[j]; }
	v_mov_b32_dpp v26, v252 row_shr:3 row_mask:0xf bank_mask:0xf
	v_mov_b32_dpp v27, v253 row_shr:3 row_mask:0xf bank_mask:0xf
	v_mov_b32_dpp v28, v246 row_ror:2 row_mask:0xf bank_mask:0xf
	v_mov_b32_dpp v29, v247 row_ror:2 row_mask:0xf bank_mask:0xf
	v_mov_b32_dpp v30, v248 row_ror:2 row_mask:0xf bank_mask:0xf
	v_mov_b32_dpp v31, v249 row_ror:2 row_mask:0xf bank_mask:0xf
	v_mov_b32_dpp v28, v250 row_shr:2 row_mask:0xf bank_mask:0xf
	v_mov_b32_dpp v29, v251 row_shr:2 row_mask:0xf bank_mask:0xf
	v_mov_b32_dpp v30, v252 row_shr:2 row_mask:0xf bank_mask:0xf
	v_mov_b32_dpp v31, v253 row_shr:2 row_mask:0xf bank_mask:0xf
	v_mov_b32_dpp v80, v246 row_ror:1 row_mask:0xf bank_mask:0xf
	v_mov_b32_dpp v81, v247 row_ror:1 row_mask:0xf bank_mask:0xf
	v_mov_b32_dpp v82, v248 row_ror:1 row_mask:0xf bank_mask:0xf
	v_mov_b32_dpp v83, v249 row_ror:1 row_mask:0xf bank_mask:0xf
	v_mov_b32_dpp v80, v250 row_shr:1 row_mask:0xf bank_mask:0xf
	v_mov_b32_dpp v81, v251 row_shr:1 row_mask:0xf bank_mask:0xf
	v_mov_b32_dpp v82, v252 row_shr:1 row_mask:0xf bank_mask:0xf
	v_mov_b32_dpp v83, v253 row_shr:1 row_mask:0xf bank_mask:0xf
	v_mov_b64_e32 v[96:97], v[250:251]
	v_mov_b64_e32 v[98:99], v[252:253]
	v_cndmask_b32_e64 v147, 0, v79, s[62:63]
	v_cndmask_b32_e64 v146, 0, v78, s[62:63]
	v_cndmask_b32_e64 v149, 0, v21, s[60:61]
	v_cndmask_b32_e64 v148, 0, v20, s[60:61]
	s_add_i32 s48, s20, s27
	s_lshl_b32 s20, s91, 7
	s_add_u32 s44, s10, s20
	s_addc_u32 s45, s11, 0
	v_lshlrev_b32_e32 v134, 16, v24
	v_lshlrev_b32_e32 v142, 16, v25
	v_and_b32_e32 v135, 0xffff0000, v24
	v_and_b32_e32 v143, 0xffff0000, v25
	v_cndmask_b32_e64 v25, 0, v77, s[62:63]
	v_cndmask_b32_e64 v24, 0, v76, s[62:63]
	v_pk_fma_f32 v[142:143], v[146:147], v[142:143], v[74:75]
	v_pk_fma_f32 v[24:25], v[24:25], v[134:135], v[72:73]
	v_lshlrev_b32_e32 v134, 16, v29
	v_lshlrev_b32_e32 v146, 16, v28
	v_and_b32_e32 v135, 0xffff0000, v29
	v_and_b32_e32 v147, 0xffff0000, v28
	v_cndmask_b32_e64 v29, 0, v23, s[60:61]
	v_cndmask_b32_e64 v28, 0, v22, s[60:61]
	v_pk_fma_f32 v[24:25], v[148:149], v[146:147], v[24:25]
	v_pk_fma_f32 v[28:29], v[28:29], v[134:135], v[142:143]
	v_lshlrev_b32_e32 v134, 16, v80
	v_lshlrev_b32_e32 v142, 16, v81
	v_and_b32_e32 v135, 0xffff0000, v80
	v_and_b32_e32 v143, 0xffff0000, v81
	v_cndmask_b32_e64 v81, 0, v93, s[58:59]
	v_cndmask_b32_e64 v80, 0, v92, s[58:59]
	v_cndmask_b32_e64 v147, 0, v95, s[58:59]
	v_cndmask_b32_e64 v146, 0, v94, s[58:59]
	v_pk_fma_f32 v[28:29], v[146:147], v[142:143], v[28:29]
	v_pk_fma_f32 v[24:25], v[80:81], v[134:135], v[24:25]
	v_lshlrev_b32_e32 v80, 16, v97
	v_lshlrev_b32_e32 v134, 16, v96
	v_and_b32_e32 v81, 0xffff0000, v97
	v_and_b32_e32 v135, 0xffff0000, v96
	v_pk_fma_f32 v[24:25], v[114:115], v[134:135], v[24:25]
	v_pk_fma_f32 v[80:81], v[106:107], v[80:81], v[28:29]
	v_cvt_pk_bf16_f32 v28, v24, v25
	v_cvt_pk_bf16_f32 v29, v80, v81
	ds_write2_b32 v125, v80, v81 offset0:34 offset1:35
	ds_write2_b32 v125, v24, v25 offset0:32 offset1:33
	v_lshlrev_b32_e32 v24, 16, v26
	v_lshlrev_b32_e32 v80, 16, v27
	v_and_b32_e32 v25, 0xffff0000, v26
	v_and_b32_e32 v81, 0xffff0000, v27
	v_cndmask_b32_e64 v27, 0, v69, s[62:63]
	v_cndmask_b32_e64 v26, 0, v68, s[62:63]
	v_cndmask_b32_e64 v97, 0, v71, s[62:63]
	v_cndmask_b32_e64 v96, 0, v70, s[62:63]
	v_pk_fma_f32 v[80:81], v[96:97], v[80:81], v[42:43]
	v_pk_fma_f32 v[24:25], v[26:27], v[24:25], v[40:41]
	v_lshlrev_b32_e32 v26, 16, v31
	v_lshlrev_b32_e32 v96, 16, v30
	v_and_b32_e32 v27, 0xffff0000, v31
	v_and_b32_e32 v97, 0xffff0000, v30
	v_cndmask_b32_e64 v31, 0, v39, s[60:61]
	v_cndmask_b32_e64 v30, 0, v38, s[60:61]
	v_cndmask_b32_e64 v135, 0, v37, s[60:61]
	v_cndmask_b32_e64 v134, 0, v36, s[60:61]
	v_pk_fma_f32 v[24:25], v[134:135], v[96:97], v[24:25]
	v_pk_fma_f32 v[26:27], v[30:31], v[26:27], v[80:81]
	v_lshlrev_b32_e32 v30, 16, v82
	v_lshlrev_b32_e32 v80, 16, v83
	v_and_b32_e32 v31, 0xffff0000, v82
	v_and_b32_e32 v81, 0xffff0000, v83
	v_cndmask_b32_e64 v83, 0, v85, s[58:59]
	v_cndmask_b32_e64 v82, 0, v84, s[58:59]
	v_cndmask_b32_e64 v97, 0, v87, s[58:59]
	v_cndmask_b32_e64 v96, 0, v86, s[58:59]
	v_pk_fma_f32 v[26:27], v[96:97], v[80:81], v[26:27]
	v_pk_fma_f32 v[24:25], v[82:83], v[30:31], v[24:25]
	v_lshlrev_b32_e32 v30, 16, v99
	v_lshlrev_b32_e32 v80, 16, v98
	v_and_b32_e32 v31, 0xffff0000, v99
	v_and_b32_e32 v81, 0xffff0000, v98
	v_pk_fma_f32 v[24:25], v[118:119], v[80:81], v[24:25]
	v_pk_fma_f32 v[26:27], v[116:117], v[30:31], v[26:27]
	v_cvt_pk_bf16_f32 v30, v24, v25
	ds_write2_b32 v125, v26, v27 offset0:38 offset1:39
	ds_write2_b32 v125, v24, v25 offset0:36 offset1:37
	v_cvt_pk_bf16_f32 v31, v26, v27
	v_mov_b32_dpp v24, v250 row_ror:3 row_mask:0xf bank_mask:0xf
	v_mov_b32_dpp v25, v251 row_ror:3 row_mask:0xf bank_mask:0xf
	v_mov_b32_dpp v26, v252 row_ror:3 row_mask:0xf bank_mask:0xf
	v_mov_b32_dpp v27, v253 row_ror:3 row_mask:0xf bank_mask:0xf
	v_mov_b32_dpp v24, v190 row_shr:3 row_mask:0xf bank_mask:0xf
	v_mov_b32_dpp v25, v191 row_shr:3 row_mask:0xf bank_mask:0xf
	v_mov_b32_dpp v26, v192 row_shr:3 row_mask:0xf bank_mask:0xf
	v_mov_b32_dpp v27, v193 row_shr:3 row_mask:0xf bank_mask:0xf
	v_mov_b32_dpp v80, v250 row_ror:2 row_mask:0xf bank_mask:0xf
	v_mov_b32_dpp v81, v251 row_ror:2 row_mask:0xf bank_mask:0xf
	v_mov_b32_dpp v82, v252 row_ror:2 row_mask:0xf bank_mask:0xf
	v_mov_b32_dpp v83, v253 row_ror:2 row_mask:0xf bank_mask:0xf
	v_mov_b32_dpp v80, v190 row_shr:2 row_mask:0xf bank_mask:0xf
	v_mov_b32_dpp v81, v191 row_shr:2 row_mask:0xf bank_mask:0xf
	v_mov_b32_dpp v82, v192 row_shr:2 row_mask:0xf bank_mask:0xf
	v_mov_b32_dpp v83, v193 row_shr:2 row_mask:0xf bank_mask:0xf
	v_mov_b32_dpp v96, v250 row_ror:1 row_mask:0xf bank_mask:0xf
; __device__ __forceinline__ void ld8bf(const bf16_t* p, float (&o)[8]) { unpack8(*(const u32x4*)p, o); }
; __device__ __forceinline__ bf16x8 pack_frag(const float (&v)[8]) { return __builtin_bit_cast(bf16x8, pack8(v)); }
; __device__ __forceinline__ void w_lru_m1(const Args& a, int l, unsigned char* ws, const bf16_t* proj, bf16_t* y, LAS unsigned char* wl, int b, int ck_, int h, int lane) {
;     ...
;         for (int tb = 0; tb < 4; ++tb) { const int tok = 16 * tb + lo, t = 64 * ck_ + tok; float s[8];
; #pragma unroll
;             for (int j = 0; j < 8; ++j) s[j] = bs[j];
; #pragma unroll
;             for (int k = 0; k < 4; ++k) { const int tt = t - 3 + k; float x[8];
;                 ld8bf(proj + (size_t)(b * SEQ + (tt >= 0 ? tt : 0)) * NIN + C_LX + ch0, x);
; #pragma unroll
;                 for (int j = 0; j < 8; ++j) s[j] += (tt >= 0 ? w[k][j] : 0.f) * x[j]; }
;             Xf[tb][kk] = pack_frag(s);
; #pragma unroll
;             for (int j = 0; j < 8; ++j) xcf[tok * 65 + 32 * kk + 8 * fq + j] = s[j]; }
	v_mov_b32_dpp v97, v251 row_ror:1 row_mask:0xf bank_mask:0xf
	v_mov_b32_dpp v98, v252 row_ror:1 row_mask:0xf bank_mask:0xf
	v_mov_b32_dpp v99, v253 row_ror:1 row_mask:0xf bank_mask:0xf
	v_mov_b32_dpp v96, v190 row_shr:1 row_mask:0xf bank_mask:0xf
	v_mov_b32_dpp v97, v191 row_shr:1 row_mask:0xf bank_mask:0xf
	v_mov_b32_dpp v98, v192 row_shr:1 row_mask:0xf bank_mask:0xf
	v_mov_b32_dpp v99, v193 row_shr:1 row_mask:0xf bank_mask:0xf
	v_mov_b64_e32 v[130:131], v[190:191]
	v_mov_b64_e32 v[132:133], v[192:193]
	v_cndmask_b32_e64 v147, 0, v79, s[56:57]
	v_cndmask_b32_e64 v146, 0, v78, s[56:57]
	v_cndmask_b32_e64 v149, 0, v21, s[54:55]
	v_cndmask_b32_e64 v148, 0, v20, s[54:55]
	v_cndmask_b32_e64 v79, 0, v79, s[46:47]
	v_cndmask_b32_e64 v78, 0, v78, s[46:47]
	v_cndmask_b32_e64 v21, 0, v21, s[40:41]
	v_cndmask_b32_e64 v20, 0, v20, s[40:41]
	v_lshlrev_b32_e32 v134, 16, v24
	v_lshlrev_b32_e32 v142, 16, v25
	v_and_b32_e32 v135, 0xffff0000, v24
	v_and_b32_e32 v143, 0xffff0000, v25
	v_cndmask_b32_e64 v25, 0, v77, s[56:57]
	v_cndmask_b32_e64 v24, 0, v76, s[56:57]
	v_pk_fma_f32 v[142:143], v[146:147], v[142:143], v[74:75]
	v_pk_fma_f32 v[24:25], v[24:25], v[134:135], v[72:73]
	v_lshlrev_b32_e32 v134, 16, v81
	v_lshlrev_b32_e32 v146, 16, v80
	v_and_b32_e32 v135, 0xffff0000, v81
	v_and_b32_e32 v147, 0xffff0000, v80
	v_cndmask_b32_e64 v81, 0, v23, s[54:55]
	v_cndmask_b32_e64 v80, 0, v22, s[54:55]
	v_pk_fma_f32 v[24:25], v[148:149], v[146:147], v[24:25]
	v_pk_fma_f32 v[80:81], v[80:81], v[134:135], v[142:143]
	v_lshlrev_b32_e32 v134, 16, v96
	v_lshlrev_b32_e32 v142, 16, v97
	v_and_b32_e32 v135, 0xffff0000, v96
	v_and_b32_e32 v143, 0xffff0000, v97
	v_cndmask_b32_e64 v97, 0, v93, s[52:53]
	v_cndmask_b32_e64 v96, 0, v92, s[52:53]
	v_cndmask_b32_e64 v147, 0, v95, s[52:53]
	v_cndmask_b32_e64 v146, 0, v94, s[52:53]
	v_pk_fma_f32 v[80:81], v[146:147], v[142:143], v[80:81]
	v_pk_fma_f32 v[24:25], v[96:97], v[134:135], v[24:25]
	v_lshlrev_b32_e32 v96, 16, v131
	v_lshlrev_b32_e32 v134, 16, v130
	v_and_b32_e32 v97, 0xffff0000, v131
	v_and_b32_e32 v135, 0xffff0000, v130
	v_pk_fma_f32 v[130:131], v[114:115], v[134:135], v[24:25]
	v_pk_fma_f32 v[80:81], v[106:107], v[96:97], v[80:81]
	v_cvt_pk_bf16_f32 v24, v130, v131
	v_cvt_pk_bf16_f32 v25, v80, v81
	ds_write2_b32 v124, v80, v81 offset0:34 offset1:35
	ds_write2_b32 v124, v130, v131 offset0:32 offset1:33
	v_lshlrev_b32_e32 v80, 16, v26
	v_lshlrev_b32_e32 v96, 16, v27
	v_and_b32_e32 v81, 0xffff0000, v26
	v_and_b32_e32 v97, 0xffff0000, v27
	v_cndmask_b32_e64 v27, 0, v69, s[56:57]
	v_cndmask_b32_e64 v26, 0, v68, s[56:57]
	v_cndmask_b32_e64 v131, 0, v71, s[56:57]
	v_cndmask_b32_e64 v130, 0, v70, s[56:57]
	v_pk_fma_f32 v[96:97], v[130:131], v[96:97], v[42:43]
	v_pk_fma_f32 v[26:27], v[26:27], v[80:81], v[40:41]
	v_lshlrev_b32_e32 v80, 16, v83
	v_lshlrev_b32_e32 v130, 16, v82
	v_and_b32_e32 v81, 0xffff0000, v83
	v_and_b32_e32 v131, 0xffff0000, v82
	v_cndmask_b32_e64 v83, 0, v39, s[54:55]
	v_cndmask_b32_e64 v82, 0, v38, s[54:55]
	v_cndmask_b32_e64 v135, 0, v37, s[54:55]
	v_cndmask_b32_e64 v134, 0, v36, s[54:55]
	v_pk_fma_f32 v[26:27], v[134:135], v[130:131], v[26:27]
	v_pk_fma_f32 v[80:81], v[82:83], v[80:81], v[96:97]
	v_lshlrev_b32_e32 v82, 16, v98
	v_lshlrev_b32_e32 v96, 16, v99
	v_and_b32_e32 v83, 0xffff0000, v98
	v_and_b32_e32 v97, 0xffff0000, v99
	v_cndmask_b32_e64 v99, 0, v85, s[52:53]
	v_cndmask_b32_e64 v98, 0, v84, s[52:53]
	v_cndmask_b32_e64 v131, 0, v87, s[52:53]
	v_cndmask_b32_e64 v130, 0, v86, s[52:53]
	v_pk_fma_f32 v[80:81], v[130:131], v[96:97], v[80:81]
	v_pk_fma_f32 v[26:27], v[98:99], v[82:83], v[26:27]
	v_lshlrev_b32_e32 v82, 16, v133
	v_and_b32_e32 v83, 0xffff0000, v133
	v_lshlrev_b32_e32 v96, 16, v132
	v_and_b32_e32 v97, 0xffff0000, v132
	v_pk_fma_f32 v[80:81], v[116:117], v[82:83], v[80:81]
	v_pk_fma_f32 v[96:97], v[118:119], v[96:97], v[26:27]
	v_cvt_pk_bf16_f32 v27, v80, v81
	ds_write2_b32 v124, v80, v81 offset0:38 offset1:39
	ds_write2_b32 v124, v96, v97 offset0:36 offset1:37
	v_mov_b32_dpp v130, v190 row_ror:3 row_mask:0xf bank_mask:0xf
	v_mov_b32_dpp v131, v191 row_ror:3 row_mask:0xf bank_mask:0xf
	v_mov_b32_dpp v132, v192 row_ror:3 row_mask:0xf bank_mask:0xf
	v_mov_b32_dpp v133, v193 row_ror:3 row_mask:0xf bank_mask:0xf
	v_mov_b32_dpp v130, v194 row_shr:3 row_mask:0xf bank_mask:0xf
	v_mov_b32_dpp v131, v195 row_shr:3 row_mask:0xf bank_mask:0xf
	v_mov_b32_dpp v132, v196 row_shr:3 row_mask:0xf bank_mask:0xf
	v_mov_b32_dpp v133, v197 row_shr:3 row_mask:0xf bank_mask:0xf
	v_mov_b32_dpp v124, v190 row_ror:2 row_mask:0xf bank_mask:0xf
	v_mov_b32_dpp v125, v191 row_ror:2 row_mask:0xf bank_mask:0xf
	v_mov_b32_dpp v126, v192 row_ror:2 row_mask:0xf bank_mask:0xf
	v_mov_b32_dpp v127, v193 row_ror:2 row_mask:0xf bank_mask:0xf
	v_mov_b32_dpp v124, v194 row_shr:2 row_mask:0xf bank_mask:0xf
	v_mov_b32_dpp v125, v195 row_shr:2 row_mask:0xf bank_mask:0xf
	v_mov_b32_dpp v126, v196 row_shr:2 row_mask:0xf bank_mask:0xf
	v_mov_b32_dpp v127, v197 row_shr:2 row_mask:0xf bank_mask:0xf
	v_cvt_pk_bf16_f32 v26, v96, v97
	v_mov_b32_dpp v96, v190 row_ror:1 row_mask:0xf bank_mask:0xf
	v_mov_b32_dpp v97, v191 row_ror:1 row_mask:0xf bank_mask:0xf
	v_mov_b32_dpp v98, v192 row_ror:1 row_mask:0xf bank_mask:0xf
	v_mov_b32_dpp v99, v193 row_ror:1 row_mask:0xf bank_mask:0xf
	v_mov_b32_dpp v96, v194 row_shr:1 row_mask:0xf bank_mask:0xf
	v_mov_b32_dpp v97, v195 row_shr:1 row_mask:0xf bank_mask:0xf
	v_mov_b32_dpp v98, v196 row_shr:1 row_mask:0xf bank_mask:0xf
	v_mov_b32_dpp v99, v197 row_shr:1 row_mask:0xf bank_mask:0xf
	v_mov_b64_e32 v[80:81], v[194:195]
	v_mov_b64_e32 v[82:83], v[196:197]
	v_cndmask_b32_e64 v77, 0, v77, s[46:47]
; __device__ __forceinline__ void ld8bf(const bf16_t* p, float (&o)[8]) { unpack8(*(const u32x4*)p, o); }
; __device__ __forceinline__ bf16x8 pack_frag(const float (&v)[8]) { return __builtin_bit_cast(bf16x8, pack8(v)); }
; __device__ __forceinline__ void w_lru_m1(const Args& a, int l, unsigned char* ws, const bf16_t* proj, bf16_t* y, LAS unsigned char* wl, int b, int ck_, int h, int lane) {
;     ...
;         for (int tb = 0; tb < 4; ++tb) { const int tok = 16 * tb + lo, t = 64 * ck_ + tok; float s[8];
; #pragma unroll
;             for (int j = 0; j < 8; ++j) s[j] = bs[j];
; #pragma unroll
;             for (int k = 0; k < 4; ++k) { const int tt = t - 3 + k; float x[8];
;                 ld8bf(proj + (size_t)(b * SEQ + (tt >= 0 ? tt : 0)) * NIN + C_LX + ch0, x);
; #pragma unroll
;                 for (int j = 0; j < 8; ++j) s[j] += (tt >= 0 ? w[k][j] : 0.f) * x[j]; }
;             Xf[tb][kk] = pack_frag(s);
; #pragma unroll
;             for (int j = 0; j < 8; ++j) xcf[tok * 65 + 32 * kk + 8 * fq + j] = s[j]; }
;     ...
;     for (int jb = 0; jb < 4; ++jb) {
;         bf16x8 WaF[2], WxF[2]; f32x4 pba, pbx, plam;
; #pragma unroll
;         for (int kk = 0; kk < 2; ++kk) { WaF[kk] = nWa[kk]; WxF[kk] = nWx[kk]; }
;         pba = nba; pbx = nbx; plam = nlam;
;         if (jb < 3) {
; #pragma unroll
;             for (int kk = 0; kk < 2; ++kk) { nWa[kk] = *(const bf16x8*)(waT + (16 * (jb + 1) + lo) * 64 + 32 * kk + 8 * fq); nWx[kk] = *(const bf16x8*)(wxT + (16 * (jb + 1) + lo) * 64 + 32 * kk + 8 * fq); }
;             nba = *(const f32x4*)(ba + 16 * (jb + 1) + 4 * fq); nbx = *(const f32x4*)(bx + 16 * (jb + 1) + 4 * fq); nlam = *(const f32x4*)(lam + 16 * (jb + 1) + 4 * fq);
;         }
;         const int j0 = 16 * jb + 4 * fq;
;         float bav[4], bxv[4], sp[4], hc[4], Pc[4];
; #pragma unroll
;         for (int r = 0; r < 4; ++r) { bav[r] = pba[r]; bxv[r] = pbx[r]; sp[r] = log1pf(__expf(-plam[r])); hc[r] = 0.f; Pc[r] = 1.f; }
; #pragma unroll
;         for (int tb = 0; tb < 4; ++tb) { const int tok = 16 * tb + lo;
;             f32x4 ga = {0.f, 0.f, 0.f, 0.f}, gx = {0.f, 0.f, 0.f, 0.f};
; #pragma unroll
;             for (int kk = 0; kk < 2; ++kk) { ga = __builtin_amdgcn_mfma_f32_16x16x32_bf16(WaF[kk], Xf[tb][kk], ga, 0, 0, 0); gx = __builtin_amdgcn_mfma_f32_16x16x32_bf16(WxF[kk], Xf[tb][kk], gx, 0, 0, 0); }
	v_cndmask_b32_e64 v76, 0, v76, s[46:47]
	v_cndmask_b32_e64 v23, 0, v23, s[40:41]
	v_cndmask_b32_e64 v22, 0, v22, s[40:41]
	v_cndmask_b32_e64 v69, 0, v69, s[46:47]
	v_cndmask_b32_e64 v68, 0, v68, s[46:47]
	v_cndmask_b32_e64 v71, 0, v71, s[46:47]
	v_cndmask_b32_e64 v70, 0, v70, s[46:47]
	v_cndmask_b32_e64 v39, 0, v39, s[40:41]
	v_cndmask_b32_e64 v38, 0, v38, s[40:41]
	v_cndmask_b32_e64 v37, 0, v37, s[40:41]
	v_cndmask_b32_e64 v36, 0, v36, s[40:41]
	s_add_u32 s46, s71, s20
	s_addc_u32 s47, s64, 0
	s_ashr_i32 s91, s90, 31
	s_lshl_b64 s[42:43], s[90:91], 9
	s_or_b32 s42, s42, s21
	v_lshlrev_b32_e32 v102, 16, v130
	v_lshlrev_b32_e32 v104, 16, v131
	v_and_b32_e32 v103, 0xffff0000, v130
	v_and_b32_e32 v105, 0xffff0000, v131
	v_pk_fma_f32 v[74:75], v[78:79], v[104:105], v[74:75]
	v_pk_fma_f32 v[72:73], v[76:77], v[102:103], v[72:73]
	v_lshlrev_b32_e32 v76, 16, v125
	v_lshlrev_b32_e32 v78, 16, v124
	v_and_b32_e32 v77, 0xffff0000, v125
	v_and_b32_e32 v79, 0xffff0000, v124
	v_pk_fma_f32 v[20:21], v[20:21], v[78:79], v[72:73]
	v_pk_fma_f32 v[22:23], v[22:23], v[76:77], v[74:75]
	v_lshlrev_b32_e32 v72, 16, v96
	v_lshlrev_b32_e32 v74, 16, v97
	v_and_b32_e32 v73, 0xffff0000, v96
	v_and_b32_e32 v75, 0xffff0000, v97
	v_cndmask_b32_e32 v77, 0, v93, vcc
	v_cndmask_b32_e32 v76, 0, v92, vcc
	v_cndmask_b32_e32 v79, 0, v95, vcc
	v_cndmask_b32_e32 v78, 0, v94, vcc
	v_pk_fma_f32 v[22:23], v[78:79], v[74:75], v[22:23]
	v_pk_fma_f32 v[20:21], v[76:77], v[72:73], v[20:21]
	v_lshlrev_b32_e32 v72, 16, v81
	v_and_b32_e32 v73, 0xffff0000, v81
	v_lshlrev_b32_e32 v74, 16, v80
	v_and_b32_e32 v75, 0xffff0000, v80
	v_pk_fma_f32 v[22:23], v[106:107], v[72:73], v[22:23]
	v_pk_fma_f32 v[74:75], v[114:115], v[74:75], v[20:21]
	v_cvt_pk_bf16_f32 v21, v22, v23
	ds_write2_b32 v120, v22, v23 offset0:34 offset1:35
	ds_write2_b32 v120, v74, v75 offset0:32 offset1:33
	v_lshlrev_b32_e32 v22, 16, v132
	v_lshlrev_b32_e32 v72, 16, v133
	v_and_b32_e32 v23, 0xffff0000, v132
	v_and_b32_e32 v73, 0xffff0000, v133
	v_pk_fma_f32 v[42:43], v[70:71], v[72:73], v[42:43]
	v_pk_fma_f32 v[22:23], v[68:69], v[22:23], v[40:41]
	v_lshlrev_b32_e32 v40, 16, v127
	v_lshlrev_b32_e32 v68, 16, v126
	v_and_b32_e32 v41, 0xffff0000, v127
	v_and_b32_e32 v69, 0xffff0000, v126
	v_pk_fma_f32 v[22:23], v[36:37], v[68:69], v[22:23]
	v_pk_fma_f32 v[36:37], v[38:39], v[40:41], v[42:43]
	v_lshlrev_b32_e32 v38, 16, v98
	v_lshlrev_b32_e32 v40, 16, v99
	v_and_b32_e32 v39, 0xffff0000, v98
	v_and_b32_e32 v41, 0xffff0000, v99
	v_cndmask_b32_e32 v43, 0, v85, vcc
	v_cndmask_b32_e32 v42, 0, v84, vcc
	v_cndmask_b32_e32 v69, 0, v87, vcc
	v_cndmask_b32_e32 v68, 0, v86, vcc
	v_pk_fma_f32 v[36:37], v[68:69], v[40:41], v[36:37]
	v_pk_fma_f32 v[22:23], v[42:43], v[38:39], v[22:23]
	v_lshlrev_b32_e32 v38, 16, v83
	v_and_b32_e32 v39, 0xffff0000, v83
	v_lshlrev_b32_e32 v40, 16, v82
	v_and_b32_e32 v41, 0xffff0000, v82
	v_pk_fma_f32 v[36:37], v[116:117], v[38:39], v[36:37]
	v_pk_fma_f32 v[40:41], v[118:119], v[40:41], v[22:23]
	v_cvt_pk_bf16_f32 v23, v36, v37
	ds_write2_b32 v120, v36, v37 offset0:38 offset1:39
	ds_write2_b32 v120, v40, v41 offset0:36 offset1:37
	v_lshlrev_b32_e32 v36, 2, v122
	v_lshl_add_u64 v[118:119], s[92:93], 0, v[100:101]
	v_lshl_add_u64 v[120:121], s[34:35], 0, v[100:101]
	v_and_b32_e32 v143, 0xc0, v36
	v_lshl_add_u64 v[36:37], v[118:119], 0, v[2:3]
	v_lshl_add_u64 v[38:39], v[120:121], 0, v[2:3]
	s_nop 7
	s_waitcnt lgkmcnt(0)
	v_cvt_pk_bf16_f32 v20, v74, v75
	v_cvt_pk_bf16_f32 v22, v40, v41
	s_nop 7
	global_load_dwordx4 v[68:71], v[36:37], off offset:2048
	global_load_dwordx4 v[72:75], v[38:39], off offset:2048
	global_load_dwordx4 v[76:79], v[36:37], off offset:2112
	global_load_dwordx4 v[80:83], v[38:39], off offset:2112
	global_load_dwordx4 v[40:43], v[108:109], off offset:64
	s_nop 7
	global_load_dwordx4 v[36:39], v[110:111], off offset:64
	global_load_dwordx4 v[84:87], v[112:113], off offset:64
	s_nop 7
	v_mov_b32_e32 v104, 1.0
	s_nop 7
	v_mov_b32_e32 v105, 1.0
	s_nop 7
	v_cmp_eq_u32_e32 vcc, 0, v136
	s_nop 7
	v_mov_b32_e32 v145, v88
	s_nop 7
	v_mov_b32_e32 v147, v89
	s_nop 7
	v_mov_b32_e32 v103, 1.0
	s_nop 7
	v_mov_b32_e32 v2, v90
	s_nop 7
	v_mov_b32_e32 v100, 1.0
	s_nop 7
	v_mov_b32_e32 v101, 1.0
	s_nop 7
	v_mfma_f32_16x16x32_bf16 v[92:95], v[56:59], v[16:19], 0
	v_mov_b32_e32 v98, 1.0
	s_nop 7
	v_mfma_f32_16x16x32_bf16 v[92:95], v[64:67], v[32:35], v[92:95]
	v_mov_b32_e32 v99, 1.0
	s_nop 7
	v_mov_b32_e32 v146, v91
	v_and_b32_e32 v88, -16, v122
	v_add_u32_e32 v142, s6, v88
	v_lshlrev_b64 v[88:89], 1, v[0:1]
	v_lshl_add_u64 v[114:115], s[44:45], 0, v[88:89]
	v_lshl_add_u64 v[116:117], s[46:47], 0, v[88:89]
	v_and_b32_e32 v198, 16, v144
	v_lshrrev_b32_e32 v199, 1, v198
	v_add_u32_e32 v198, v198, v199
	v_mov_b32_e32 v199, 0
	v_lshl_add_u64 v[114:115], v[114:115], 0, v[198:199]
	v_lshl_add_u64 v[116:117], v[116:117], 0, v[198:199]
	v_mfma_f32_16x16x32_bf16 v[88:91], v[52:55], v[16:19], 0
	v_mad_u32_u24 v122, v136, s76, v142
	ds_read2_b32 v[124:125], v122 offset1:1
	ds_read2_b32 v[128:129], v122 offset0:2 offset1:3
	v_mfma_f32_16x16x32_bf16 v[88:91], v[60:63], v[32:35], v[88:91]
	v_mov_b32_e32 v102, 1.0
	v_add_u32_e32 v148, v142, v123
	v_add_u32_e32 v150, v142, v141
	s_nop 4
	v_add_f32_e32 v88, v48, v88
	v_add_f32_e32 v89, v49, v89
	v_mul_f32_e32 v88, 0xbfb8aa3b, v88
	v_mul_f32_e32 v89, 0xbfb8aa3b, v89
	v_exp_f32_e32 v88, v88
	v_exp_f32_e32 v89, v89
	v_add_f32_e32 v90, v50, v90
	v_mul_f32_e32 v90, 0xbfb8aa3b, v90
	v_add_f32_e32 v88, 1.0, v88
	v_add_f32_e32 v89, 1.0, v89
	v_rcp_f32_e32 v96, v88
	v_rcp_f32_e32 v97, v89
	v_add_f32_e32 v88, v44, v92
	v_add_f32_e32 v89, v45, v93
	v_mul_f32_e32 v92, 0xc1000000, v96
	v_mul_f32_e32 v93, 0xc1000000, v97
	v_mul_f32_e32 v88, 0xbfb8aa3b, v88
	v_mul_f32_e32 v92, v145, v92
	v_mul_f32_e32 v89, 0xbfb8aa3b, v89
	v_mul_f32_e32 v93, v147, v93
	v_exp_f32_e32 v88, v88
	v_mul_f32_e32 v92, 0x3fb8aa3b, v92
	v_exp_f32_e32 v89, v89
	v_mul_f32_e32 v93, 0x3fb8aa3b, v93
	v_exp_f32_e32 v92, v92
	v_exp_f32_e32 v93, v93
	v_add_f32_e32 v88, 1.0, v88
	v_add_f32_e32 v89, 1.0, v89
	v_rcp_f32_e32 v88, v88
	v_fma_f32 v96, -v92, v92, 1.0
	v_rcp_f32_e32 v89, v89
	v_fma_f32 v97, -v93, v93, 1.0
	v_sqrt_f32_e32 v96, v96
	v_sqrt_f32_e32 v97, v97
	s_waitcnt lgkmcnt(0)
; __device__ __forceinline__ unsigned pk2(float lo, float hi) { const f32x2_t v = {lo, hi}; const bf16x2_t b = __builtin_convertvector(v, bf16x2_t); return __builtin_bit_cast(unsigned, b); }
; __device__ __forceinline__ float sigmoidf_(float x) { return __builtin_amdgcn_rcpf(1.0f + __expf(-x)); }
; __device__ __forceinline__ float bcast15(float v, int lane) { return bperm_f((lane & 48) | 15, v); }
; __device__ __forceinline__ void w_lru_m1(const Args& a, int l, unsigned char* ws, const bf16_t* proj, bf16_t* y, LAS unsigned char* wl, int b, int ck_, int h, int lane) {
;     ...
;             for (int kk = 0; kk < 2; ++kk) { ga = __builtin_amdgcn_mfma_f32_16x16x32_bf16(WaF[kk], Xf[tb][kk], ga, 0, 0, 0); gx = __builtin_amdgcn_mfma_f32_16x16x32_bf16(WxF[kk], Xf[tb][kk], gx, 0, 0, 0); }
;             float hv[4], pv[4];
; #pragma unroll
;             for (int r = 0; r < 4; ++r) {
;                 const float rg = sigmoidf_(ga[r] + bav[r]), ig = sigmoidf_(gx[r] + bxv[r]);
;                 const float la = -8.0f * rg * sp[r]; float A = __expf(la);
;                 float U = __builtin_amdgcn_sqrtf(1.0f - A * A) * (ig * xcf[tok * 65 + j0 + r]);
;                 { const float As = dpp_shr1<1>(A), Us = dpp_shr0<1>(U); U = A * Us + U; A = A * As; }
;                 { const float As = dpp_shr1<2>(A), Us = dpp_shr0<2>(U); U = A * Us + U; A = A * As; }
;                 { const float As = dpp_shr1<4>(A), Us = dpp_shr0<4>(U); U = A * Us + U; A = A * As; }
;                 { const float As = dpp_shr1<8>(A), Us = dpp_shr0<8>(U); U = A * Us + U; A = A * As; }
;                 const float hh = U + A * hc[r], PP = A * Pc[r];
;                 hc[r] = bcast15(hh, lane); Pc[r] = bcast15(PP, lane); hv[r] = hh; pv[r] = PP; }
;             *(unsigned long long*)(y + (size_t)(row0 + tok) * DM + 64 * h + j0) = (unsigned long long)pk2(hv[0], hv[1]) | ((unsigned long long)pk2(hv[2], hv[3]) << 32);
;             *(unsigned long long*)((bf16_t*)(ws + WS_P) + (size_t)(row0 + tok) * 512 + 64 * h + j0) = (unsigned long long)pk2(pv[0], pv[1]) | ((unsigned long long)pk2(pv[2], pv[3]) << 32);
	v_pk_mul_f32 v[88:89], v[124:125], v[88:89]
	v_mov_b32_dpp v98, v92 row_shr:1 row_mask:0xf bank_mask:0xf
	v_mov_b32_dpp v99, v93 row_shr:1 row_mask:0xf bank_mask:0xf
	v_pk_mul_f32 v[88:89], v[88:89], v[96:97]
	v_pk_mul_f32 v[98:99], v[92:93], v[98:99]
	v_exp_f32_e32 v90, v90
	v_mov_b32_dpp v96, v88 row_shr:1 row_mask:0xf bank_mask:0xf bound_ctrl:1
	v_mov_b32_dpp v97, v89 row_shr:1 row_mask:0xf bank_mask:0xf bound_ctrl:1
	v_pk_fma_f32 v[88:89], v[92:93], v[96:97], v[88:89]
	v_mov_b32_dpp v100, v98 row_shr:2 row_mask:0xf bank_mask:0xf
	v_mov_b32_dpp v101, v99 row_shr:2 row_mask:0xf bank_mask:0xf
	v_mov_b32_dpp v92, v88 row_shr:2 row_mask:0xf bank_mask:0xf bound_ctrl:1
	v_mov_b32_dpp v93, v89 row_shr:2 row_mask:0xf bank_mask:0xf bound_ctrl:1
	v_pk_fma_f32 v[88:89], v[98:99], v[92:93], v[88:89]
	v_pk_mul_f32 v[100:101], v[98:99], v[100:101]
	v_add_f32_e32 v90, 1.0, v90
	v_mov_b32_dpp v92, v88 row_shr:4 row_mask:0xf bank_mask:0xf bound_ctrl:1
	v_mov_b32_dpp v93, v89 row_shr:4 row_mask:0xf bank_mask:0xf bound_ctrl:1
	v_mov_b32_dpp v102, v100 row_shr:4 row_mask:0xf bank_mask:0xf
	v_mov_b32_dpp v103, v101 row_shr:4 row_mask:0xf bank_mask:0xf
	v_pk_fma_f32 v[88:89], v[100:101], v[92:93], v[88:89]
	v_pk_mul_f32 v[102:103], v[100:101], v[102:103]
	v_add_f32_e32 v91, v51, v91
	v_mov_b32_dpp v92, v88 row_shr:8 row_mask:0xf bank_mask:0xf bound_ctrl:1
	v_mov_b32_dpp v93, v89 row_shr:8 row_mask:0xf bank_mask:0xf bound_ctrl:1
	v_pk_fma_f32 v[88:89], v[102:103], v[92:93], v[88:89]
	v_rcp_f32_e32 v92, v90
	v_mul_f32_e32 v91, 0xbfb8aa3b, v91
	v_exp_f32_e32 v91, v91
	v_add_f32_e32 v90, v46, v94
	v_mul_f32_e32 v92, 0xc1000000, v92
	v_mul_f32_e32 v92, v2, v92
	v_mul_f32_e32 v92, 0x3fb8aa3b, v92
	v_exp_f32_e32 v92, v92
	v_add_f32_e32 v91, 1.0, v91
	v_mul_f32_e32 v90, 0xbfb8aa3b, v90
	v_exp_f32_e32 v90, v90
	v_fma_f32 v93, -v92, v92, 1.0
	v_sqrt_f32_e32 v94, v93
	v_rcp_f32_e32 v93, v91
	v_add_f32_e32 v91, v47, v95
	v_mul_f32_e32 v91, 0xbfb8aa3b, v91
	v_exp_f32_e32 v91, v91
	v_mul_f32_e32 v93, 0xc1000000, v93
	v_mul_f32_e32 v93, v146, v93
	v_mul_f32_e32 v93, 0x3fb8aa3b, v93
	v_exp_f32_e32 v93, v93
	v_add_f32_e32 v90, 1.0, v90
	v_add_f32_e32 v91, 1.0, v91
	v_rcp_f32_e32 v90, v90
	v_rcp_f32_e32 v91, v91
	v_fma_f32 v95, -v93, v93, 1.0
	v_sqrt_f32_e32 v95, v95
	v_mov_b32_e32 v96, 1.0
	v_pk_mul_f32 v[90:91], v[90:91], v[128:129]
	v_mov_b32_e32 v97, 1.0
	v_pk_mul_f32 v[90:91], v[94:95], v[90:91]
	v_mov_b32_dpp v96, v92 row_shr:1 row_mask:0xf bank_mask:0xf
	v_mov_b32_dpp v97, v93 row_shr:1 row_mask:0xf bank_mask:0xf
	v_mov_b32_dpp v94, v90 row_shr:1 row_mask:0xf bank_mask:0xf bound_ctrl:1
	v_mov_b32_dpp v95, v91 row_shr:1 row_mask:0xf bank_mask:0xf bound_ctrl:1
	v_pk_mul_f32 v[96:97], v[92:93], v[96:97]
	v_mov_b32_e32 v100, 1.0
	v_mov_b32_e32 v101, 1.0
	v_pk_fma_f32 v[90:91], v[92:93], v[94:95], v[90:91]
	v_mov_b32_dpp v104, v102 row_shr:8 row_mask:0xf bank_mask:0xf
	v_mov_b32_dpp v105, v103 row_shr:8 row_mask:0xf bank_mask:0xf
	v_mov_b32_dpp v100, v96 row_shr:2 row_mask:0xf bank_mask:0xf
	v_mov_b32_dpp v101, v97 row_shr:2 row_mask:0xf bank_mask:0xf
	v_mov_b32_dpp v92, v90 row_shr:2 row_mask:0xf bank_mask:0xf bound_ctrl:1
	v_mov_b32_dpp v93, v91 row_shr:2 row_mask:0xf bank_mask:0xf bound_ctrl:1
	v_pk_mul_f32 v[106:107], v[102:103], v[104:105]
	v_pk_mul_f32 v[100:101], v[96:97], v[100:101]
	v_mov_b32_e32 v102, 1.0
	v_mov_b32_e32 v103, 1.0
	v_pk_fma_f32 v[90:91], v[96:97], v[92:93], v[90:91]
	v_mov_b32_dpp v102, v100 row_shr:4 row_mask:0xf bank_mask:0xf
	v_mov_b32_dpp v103, v101 row_shr:4 row_mask:0xf bank_mask:0xf
	v_mov_b32_dpp v92, v90 row_shr:4 row_mask:0xf bank_mask:0xf bound_ctrl:1
	v_mov_b32_dpp v93, v91 row_shr:4 row_mask:0xf bank_mask:0xf bound_ctrl:1
	v_pk_mul_f32 v[102:103], v[100:101], v[102:103]
	v_mov_b32_e32 v124, 1.0
	v_mov_b32_e32 v125, 1.0
	v_pk_fma_f32 v[90:91], v[100:101], v[92:93], v[90:91]
	v_mov_b32_dpp v124, v102 row_shr:8 row_mask:0xf bank_mask:0xf
	v_mov_b32_dpp v125, v103 row_shr:8 row_mask:0xf bank_mask:0xf
	v_mov_b32_dpp v92, v90 row_shr:8 row_mask:0xf bank_mask:0xf bound_ctrl:1
	v_mov_b32_dpp v93, v91 row_shr:8 row_mask:0xf bank_mask:0xf bound_ctrl:1
	v_pk_mul_f32 v[126:127], v[102:103], v[124:125]
	v_pk_fma_f32 v[90:91], v[102:103], v[92:93], v[90:91]
	v_pk_fma_f32 v[88:89], v[106:107], 0, v[88:89] op_sel_hi:[1,0,1]
	v_pk_fma_f32 v[90:91], v[126:127], 0, v[90:91] op_sel_hi:[1,0,1]
	ds_bpermute_b32 v98, v143, v88 offset:60
	ds_bpermute_b32 v99, v143, v89 offset:60
	ds_bpermute_b32 v96, v143, v90 offset:60
	v_cvt_pk_bf16_f32 v88, v88, v89
	v_cvt_pk_bf16_f32 v89, v90, v91
	v_or_b32_e32 v90, s48, v136
	ds_bpermute_b32 v97, v143, v91 offset:60
	v_ashrrev_i32_e32 v91, 31, v90
	v_lshlrev_b64 v[92:93], 11, v[90:91]
	v_lshl_add_u64 v[100:101], v[114:115], 0, v[92:93]
	v_lshlrev_b64 v[90:91], 10, v[90:91]
	v_mov_b64_e32 v[222:223], v[88:89]
	v_cvt_pk_bf16_f32 v88, v106, v107
	v_cvt_pk_bf16_f32 v89, v126, v127
	v_lshl_add_u64 v[102:103], v[116:117], 0, v[90:91]
	v_mov_b64_e32 v[226:227], v[88:89]
	v_mfma_f32_16x16x32_bf16 v[88:91], v[52:55], v[12:15], 0
	ds_bpermute_b32 v124, v143, v126 offset:60
	ds_bpermute_b32 v125, v143, v127 offset:60
	ds_bpermute_b32 v104, v143, v106 offset:60
	v_mfma_f32_16x16x32_bf16 v[126:129], v[56:59], v[12:15], 0
	ds_bpermute_b32 v105, v143, v107 offset:60
	v_mfma_f32_16x16x32_bf16 v[92:95], v[60:63], v[28:31], v[88:91]
	v_mfma_f32_16x16x32_bf16 v[88:91], v[64:67], v[28:31], v[126:129]
	s_nop 6
	v_add_f32_e32 v92, v48, v92
	v_mul_f32_e32 v92, 0xbfb8aa3b, v92
	v_exp_f32_e32 v92, v92
	v_add_f32_e32 v88, v44, v88
	v_mul_f32_e32 v88, 0xbfb8aa3b, v88
	v_exp_f32_e32 v88, v88
	v_add_f32_e32 v92, 1.0, v92
	v_rcp_f32_e32 v92, v92
; __device__ __forceinline__ float sigmoidf_(float x) { return __builtin_amdgcn_rcpf(1.0f + __expf(-x)); }
; __device__ __forceinline__ float bcast15(float v, int lane) { return bperm_f((lane & 48) | 15, v); }
; __device__ __forceinline__ void w_lru_m1(const Args& a, int l, unsigned char* ws, const bf16_t* proj, bf16_t* y, LAS unsigned char* wl, int b, int ck_, int h, int lane) {
;     ...
;         for (int tb = 0; tb < 4; ++tb) { const int tok = 16 * tb + lo;
;             f32x4 ga = {0.f, 0.f, 0.f, 0.f}, gx = {0.f, 0.f, 0.f, 0.f};
; #pragma unroll
;             for (int kk = 0; kk < 2; ++kk) { ga = __builtin_amdgcn_mfma_f32_16x16x32_bf16(WaF[kk], Xf[tb][kk], ga, 0, 0, 0); gx = __builtin_amdgcn_mfma_f32_16x16x32_bf16(WxF[kk], Xf[tb][kk], gx, 0, 0, 0); }
;             float hv[4], pv[4];
; #pragma unroll
;             for (int r = 0; r < 4; ++r) {
;                 const float rg = sigmoidf_(ga[r] + bav[r]), ig = sigmoidf_(gx[r] + bxv[r]);
;                 const float la = -8.0f * rg * sp[r]; float A = __expf(la);
;                 float U = __builtin_amdgcn_sqrtf(1.0f - A * A) * (ig * xcf[tok * 65 + j0 + r]);
;                 { const float As = dpp_shr1<1>(A), Us = dpp_shr0<1>(U); U = A * Us + U; A = A * As; }
;                 { const float As = dpp_shr1<2>(A), Us = dpp_shr0<2>(U); U = A * Us + U; A = A * As; }
;                 { const float As = dpp_shr1<4>(A), Us = dpp_shr0<4>(U); U = A * Us + U; A = A * As; }
;                 { const float As = dpp_shr1<8>(A), Us = dpp_shr0<8>(U); U = A * Us + U; A = A * As; }
;                 const float hh = U + A * hc[r], PP = A * Pc[r];
;                 hc[r] = bcast15(hh, lane); Pc[r] = bcast15(PP, lane); hv[r] = hh; pv[r] = PP; }
	v_add_f32_e32 v89, v45, v89
	v_add_f32_e32 v88, 1.0, v88
	v_rcp_f32_e32 v106, v88
	v_mul_f32_e32 v88, 0xc1000000, v92
	v_add_f32_e32 v92, v49, v93
	v_mul_f32_e32 v92, 0xbfb8aa3b, v92
	v_exp_f32_e32 v92, v92
	v_mul_f32_e32 v89, 0xbfb8aa3b, v89
	v_exp_f32_e32 v89, v89
	v_mul_f32_e32 v88, v145, v88
	v_add_f32_e32 v92, 1.0, v92
	v_rcp_f32_e32 v92, v92
	v_add_f32_e32 v89, 1.0, v89
	v_rcp_f32_e32 v107, v89
	v_mul_f32_e32 v88, 0x3fb8aa3b, v88
	v_mul_f32_e32 v89, 0xc1000000, v92
	v_mul_f32_e32 v89, v147, v89
	v_mul_f32_e32 v89, 0x3fb8aa3b, v89
	v_exp_f32_e32 v122, v88
	v_exp_f32_e32 v123, v89
	v_add_f32_e32 v94, v50, v94
	v_add_f32_e32 v95, v51, v95
	v_fma_f32 v88, -v122, v122, 1.0
	v_fma_f32 v89, -v123, v123, 1.0
	v_sqrt_f32_e32 v126, v88
	v_mov_b32_e32 v88, 1.0
	v_sqrt_f32_e32 v127, v89
	v_mov_b32_e32 v89, 1.0
	v_mov_b32_dpp v88, v122 row_shr:1 row_mask:0xf bank_mask:0xf
	v_mul_f32_e32 v94, 0xbfb8aa3b, v94
	v_mov_b32_dpp v89, v123 row_shr:1 row_mask:0xf bank_mask:0xf
	v_pk_mul_f32 v[128:129], v[122:123], v[88:89]
	v_mov_b32_e32 v88, 1.0
	v_mov_b32_e32 v89, 1.0
	v_mul_f32_e32 v95, 0xbfb8aa3b, v95
	v_mov_b32_dpp v88, v128 row_shr:2 row_mask:0xf bank_mask:0xf
	v_mov_b32_dpp v89, v129 row_shr:2 row_mask:0xf bank_mask:0xf
	v_pk_mul_f32 v[130:131], v[128:129], v[88:89]
	v_mov_b32_e32 v88, 1.0
	v_mov_b32_e32 v89, 1.0
	v_exp_f32_e32 v94, v94
	v_mov_b32_dpp v88, v130 row_shr:4 row_mask:0xf bank_mask:0xf
	v_mov_b32_dpp v89, v131 row_shr:4 row_mask:0xf bank_mask:0xf
	v_pk_mul_f32 v[132:133], v[130:131], v[88:89]
	v_mov_b32_e32 v88, 1.0
	v_mov_b32_e32 v89, 1.0
	v_exp_f32_e32 v95, v95
	v_mov_b32_dpp v88, v132 row_shr:8 row_mask:0xf bank_mask:0xf
	v_mov_b32_dpp v89, v133 row_shr:8 row_mask:0xf bank_mask:0xf
	v_pk_mul_f32 v[134:135], v[132:133], v[88:89]
	v_add_f32_e32 v90, v46, v90
	s_waitcnt lgkmcnt(0)
	v_pk_mul_f32 v[92:93], v[134:135], v[104:105]
	ds_read2_b32 v[104:105], v148 offset1:1
	v_add_f32_e32 v91, v47, v91
	v_mul_f32_e32 v90, 0xbfb8aa3b, v90
	v_mul_f32_e32 v91, 0xbfb8aa3b, v91
	v_add_f32_e32 v94, 1.0, v94
	s_waitcnt lgkmcnt(0)
	v_pk_mul_f32 v[104:105], v[104:105], v[106:107]
	v_exp_f32_e32 v90, v90
	v_pk_mul_f32 v[104:105], v[104:105], v[126:127]
	v_add_f32_e32 v95, 1.0, v95
	v_exp_f32_e32 v91, v91
	v_mov_b32_dpp v106, v104 row_shr:1 row_mask:0xf bank_mask:0xf bound_ctrl:1
	v_mov_b32_dpp v107, v105 row_shr:1 row_mask:0xf bank_mask:0xf bound_ctrl:1
	v_pk_fma_f32 v[104:105], v[122:123], v[106:107], v[104:105]
	v_rcp_f32_e32 v94, v94
	v_rcp_f32_e32 v95, v95
	v_mov_b32_dpp v106, v104 row_shr:2 row_mask:0xf bank_mask:0xf bound_ctrl:1
	v_mov_b32_dpp v107, v105 row_shr:2 row_mask:0xf bank_mask:0xf bound_ctrl:1
	v_pk_fma_f32 v[104:105], v[128:129], v[106:107], v[104:105]
	v_add_f32_e32 v90, 1.0, v90
	v_add_f32_e32 v91, 1.0, v91
	v_mov_b32_dpp v106, v104 row_shr:4 row_mask:0xf bank_mask:0xf bound_ctrl:1
	v_mov_b32_dpp v107, v105 row_shr:4 row_mask:0xf bank_mask:0xf bound_ctrl:1
	v_pk_fma_f32 v[104:105], v[130:131], v[106:107], v[104:105]
	ds_bpermute_b32 v88, v143, v92 offset:60
	ds_bpermute_b32 v89, v143, v93 offset:60
	v_mov_b32_dpp v106, v104 row_shr:8 row_mask:0xf bank_mask:0xf bound_ctrl:1
	v_mov_b32_dpp v107, v105 row_shr:8 row_mask:0xf bank_mask:0xf bound_ctrl:1
	v_pk_fma_f32 v[104:105], v[132:133], v[106:107], v[104:105]
	v_rcp_f32_e32 v106, v90
	v_mul_f32_e32 v90, 0xc1000000, v94
	v_rcp_f32_e32 v107, v91
	v_mul_f32_e32 v91, 0xc1000000, v95
	v_mul_f32_e32 v90, v2, v90
	v_mul_f32_e32 v91, v146, v91
	v_mul_f32_e32 v90, 0x3fb8aa3b, v90
	v_mul_f32_e32 v91, 0x3fb8aa3b, v91
	v_exp_f32_e32 v94, v90
	v_exp_f32_e32 v95, v91
	v_pk_fma_f32 v[104:105], v[134:135], v[98:99], v[104:105]
	ds_read2_b32 v[134:135], v148 offset0:2 offset1:3
	v_fma_f32 v90, -v94, v94, 1.0
	v_fma_f32 v91, -v95, v95, 1.0
	v_sqrt_f32_e32 v122, v90
	v_sqrt_f32_e32 v123, v91
	s_waitcnt lgkmcnt(0)
	v_pk_mul_f32 v[106:107], v[106:107], v[134:135]
	v_mov_b32_e32 v90, 1.0
	v_mov_b32_e32 v91, 1.0
	v_pk_mul_f32 v[106:107], v[122:123], v[106:107]
	v_mov_b32_dpp v90, v94 row_shr:1 row_mask:0xf bank_mask:0xf
	v_mov_b32_dpp v91, v95 row_shr:1 row_mask:0xf bank_mask:0xf
	v_mov_b32_dpp v122, v106 row_shr:1 row_mask:0xf bank_mask:0xf bound_ctrl:1
	v_mov_b32_dpp v123, v107 row_shr:1 row_mask:0xf bank_mask:0xf bound_ctrl:1
	v_pk_mul_f32 v[126:127], v[94:95], v[90:91]
	v_mov_b32_e32 v90, 1.0
	v_mov_b32_e32 v91, 1.0
	v_pk_fma_f32 v[94:95], v[94:95], v[122:123], v[106:107]
	v_mov_b32_dpp v90, v126 row_shr:2 row_mask:0xf bank_mask:0xf
	v_mov_b32_dpp v91, v127 row_shr:2 row_mask:0xf bank_mask:0xf
	v_mov_b32_dpp v106, v94 row_shr:2 row_mask:0xf bank_mask:0xf bound_ctrl:1
	v_mov_b32_dpp v107, v95 row_shr:2 row_mask:0xf bank_mask:0xf bound_ctrl:1
	v_pk_mul_f32 v[128:129], v[126:127], v[90:91]
	v_mov_b32_e32 v90, 1.0
	v_mov_b32_e32 v91, 1.0
	v_pk_fma_f32 v[94:95], v[126:127], v[106:107], v[94:95]
	v_mov_b32_dpp v90, v128 row_shr:4 row_mask:0xf bank_mask:0xf
	v_mov_b32_dpp v91, v129 row_shr:4 row_mask:0xf bank_mask:0xf
	v_mov_b32_dpp v106, v94 row_shr:4 row_mask:0xf bank_mask:0xf bound_ctrl:1
	v_mov_b32_dpp v107, v95 row_shr:4 row_mask:0xf bank_mask:0xf bound_ctrl:1
	v_pk_mul_f32 v[130:131], v[128:129], v[90:91]
	v_mov_b32_e32 v90, 1.0
	v_mov_b32_e32 v91, 1.0
	v_pk_fma_f32 v[94:95], v[128:129], v[106:107], v[94:95]
	v_mov_b32_dpp v90, v130 row_shr:8 row_mask:0xf bank_mask:0xf
	v_mov_b32_dpp v91, v131 row_shr:8 row_mask:0xf bank_mask:0xf
	v_mov_b32_dpp v106, v94 row_shr:8 row_mask:0xf bank_mask:0xf bound_ctrl:1
	v_mov_b32_dpp v107, v95 row_shr:8 row_mask:0xf bank_mask:0xf bound_ctrl:1
	v_pk_mul_f32 v[132:133], v[130:131], v[90:91]
	v_pk_fma_f32 v[94:95], v[130:131], v[106:107], v[94:95]
; __device__ __forceinline__ unsigned pk2(float lo, float hi) { const f32x2_t v = {lo, hi}; const bf16x2_t b = __builtin_convertvector(v, bf16x2_t); return __builtin_bit_cast(unsigned, b); }
; __device__ __forceinline__ float sigmoidf_(float x) { return __builtin_amdgcn_rcpf(1.0f + __expf(-x)); }
; __device__ __forceinline__ float bcast15(float v, int lane) { return bperm_f((lane & 48) | 15, v); }
; __device__ __forceinline__ void w_lru_m1(const Args& a, int l, unsigned char* ws, const bf16_t* proj, bf16_t* y, LAS unsigned char* wl, int b, int ck_, int h, int lane) {
;     ...
;         for (int tb = 0; tb < 4; ++tb) { const int tok = 16 * tb + lo;
;             f32x4 ga = {0.f, 0.f, 0.f, 0.f}, gx = {0.f, 0.f, 0.f, 0.f};
; #pragma unroll
;             for (int kk = 0; kk < 2; ++kk) { ga = __builtin_amdgcn_mfma_f32_16x16x32_bf16(WaF[kk], Xf[tb][kk], ga, 0, 0, 0); gx = __builtin_amdgcn_mfma_f32_16x16x32_bf16(WxF[kk], Xf[tb][kk], gx, 0, 0, 0); }
;             float hv[4], pv[4];
; #pragma unroll
;             for (int r = 0; r < 4; ++r) {
;                 const float rg = sigmoidf_(ga[r] + bav[r]), ig = sigmoidf_(gx[r] + bxv[r]);
;                 const float la = -8.0f * rg * sp[r]; float A = __expf(la);
;                 float U = __builtin_amdgcn_sqrtf(1.0f - A * A) * (ig * xcf[tok * 65 + j0 + r]);
;                 { const float As = dpp_shr1<1>(A), Us = dpp_shr0<1>(U); U = A * Us + U; A = A * As; }
;                 { const float As = dpp_shr1<2>(A), Us = dpp_shr0<2>(U); U = A * Us + U; A = A * As; }
;                 { const float As = dpp_shr1<4>(A), Us = dpp_shr0<4>(U); U = A * Us + U; A = A * As; }
;                 { const float As = dpp_shr1<8>(A), Us = dpp_shr0<8>(U); U = A * Us + U; A = A * As; }
;                 const float hh = U + A * hc[r], PP = A * Pc[r];
;                 hc[r] = bcast15(hh, lane); Pc[r] = bcast15(PP, lane); hv[r] = hh; pv[r] = PP; }
;             *(unsigned long long*)(y + (size_t)(row0 + tok) * DM + 64 * h + j0) = (unsigned long long)pk2(hv[0], hv[1]) | ((unsigned long long)pk2(hv[2], hv[3]) << 32);
;             *(unsigned long long*)((bf16_t*)(ws + WS_P) + (size_t)(row0 + tok) * 512 + 64 * h + j0) = (unsigned long long)pk2(pv[0], pv[1]) | ((unsigned long long)pk2(pv[2], pv[3]) << 32);
	ds_bpermute_b32 v98, v143, v104 offset:60
	v_pk_fma_f32 v[94:95], v[132:133], v[96:97], v[94:95]
	ds_bpermute_b32 v96, v143, v94 offset:60
	v_cvt_pk_bf16_f32 v107, v94, v95
	v_or_b32_e32 v94, s48, v140
	ds_bpermute_b32 v97, v143, v95 offset:60
	v_ashrrev_i32_e32 v95, 31, v94
	ds_bpermute_b32 v99, v143, v105 offset:60
	v_cvt_pk_bf16_f32 v106, v104, v105
	v_lshlrev_b64 v[104:105], 11, v[94:95]
	v_pk_mul_f32 v[124:125], v[132:133], v[124:125]
	v_lshl_add_u64 v[104:105], v[114:115], 0, v[104:105]
	v_lshlrev_b64 v[94:95], 10, v[94:95]
	v_mov_b64_e32 v[230:231], v[106:107]
	v_cvt_pk_bf16_f32 v92, v92, v93
	v_cvt_pk_bf16_f32 v93, v124, v125
	v_lshl_add_u64 v[106:107], v[116:117], 0, v[94:95]
	v_mov_b64_e32 v[234:235], v[92:93]
	v_mfma_f32_16x16x32_bf16 v[92:95], v[52:55], v[8:11], 0
	ds_bpermute_b32 v90, v143, v124 offset:60
	ds_bpermute_b32 v91, v143, v125 offset:60
	v_mfma_f32_16x16x32_bf16 v[126:129], v[60:63], v[24:27], v[92:95]
	v_mfma_f32_16x16x32_bf16 v[122:125], v[56:59], v[8:11], 0
	v_mfma_f32_16x16x32_bf16 v[122:125], v[64:67], v[24:27], v[122:125]
	s_nop 5
	v_add_f32_e32 v92, v48, v126
	v_mul_f32_e32 v92, 0xbfb8aa3b, v92
	v_exp_f32_e32 v92, v92
	v_mfma_f32_16x16x32_bf16 v[52:55], v[52:55], v[4:7], 0
	v_add_f32_e32 v92, 1.0, v92
	v_rcp_f32_e32 v93, v92
	v_add_f32_e32 v92, v44, v122
	v_mov_b32_e32 v122, 1.0
	v_mul_f32_e32 v92, 0xbfb8aa3b, v92
	v_mul_f32_e32 v93, 0xc1000000, v93
	v_mul_f32_e32 v93, v145, v93
	v_mul_f32_e32 v93, 0x3fb8aa3b, v93
	v_exp_f32_e32 v94, v93
	v_exp_f32_e32 v92, v92
	v_fma_f32 v93, -v94, v94, 1.0
	v_sqrt_f32_e32 v126, v93
	v_add_f32_e32 v93, v49, v127
	v_mul_f32_e32 v93, 0xbfb8aa3b, v93
	v_exp_f32_e32 v93, v93
	v_mov_b32_dpp v122, v94 row_shr:1 row_mask:0xf bank_mask:0xf
	v_add_f32_e32 v92, 1.0, v92
	v_rcp_f32_e32 v92, v92
	v_add_f32_e32 v93, 1.0, v93
	v_rcp_f32_e32 v95, v93
	v_add_f32_e32 v93, v45, v123
	v_mul_f32_e32 v93, 0xbfb8aa3b, v93
	v_exp_f32_e32 v93, v93
	v_mul_f32_e32 v95, 0xc1000000, v95
	v_mul_f32_e32 v95, v147, v95
	v_mul_f32_e32 v95, 0x3fb8aa3b, v95
	v_exp_f32_e32 v95, v95
	v_add_f32_e32 v93, 1.0, v93
	v_rcp_f32_e32 v93, v93
	v_fma_f32 v123, -v95, v95, 1.0
	v_sqrt_f32_e32 v127, v123
	v_mov_b32_e32 v123, 1.0
	s_nop 1
	v_mov_b32_dpp v123, v95 row_shr:1 row_mask:0xf bank_mask:0xf
	v_pk_mul_f32 v[130:131], v[94:95], v[122:123]
	v_mov_b32_e32 v122, 1.0
	v_mov_b32_e32 v123, 1.0
	s_nop 0
	v_mov_b32_dpp v122, v130 row_shr:2 row_mask:0xf bank_mask:0xf
	v_mov_b32_dpp v123, v131 row_shr:2 row_mask:0xf bank_mask:0xf
	v_pk_mul_f32 v[132:133], v[130:131], v[122:123]
	v_mov_b32_e32 v122, 1.0
	v_mov_b32_e32 v123, 1.0
	s_nop 0
	v_mov_b32_dpp v122, v132 row_shr:4 row_mask:0xf bank_mask:0xf
	v_mov_b32_dpp v123, v133 row_shr:4 row_mask:0xf bank_mask:0xf
	v_pk_mul_f32 v[134:135], v[132:133], v[122:123]
	v_mov_b32_e32 v122, 1.0
	v_mov_b32_e32 v123, 1.0
	s_nop 0
	v_mov_b32_dpp v122, v134 row_shr:8 row_mask:0xf bank_mask:0xf
	v_mov_b32_dpp v123, v135 row_shr:8 row_mask:0xf bank_mask:0xf
	v_pk_mul_f32 v[140:141], v[134:135], v[122:123]
	s_nop 0
	v_pk_mul_f32 v[148:149], v[140:141], v[88:89]
	ds_read2_b32 v[88:89], v150 offset1:1
	ds_bpermute_b32 v122, v143, v148 offset:60
	ds_bpermute_b32 v123, v143, v149 offset:60
	s_waitcnt lgkmcnt(0)
	v_pk_mul_f32 v[88:89], v[88:89], v[92:93]
	s_nop 0
	v_pk_mul_f32 v[88:89], v[88:89], v[126:127]
	s_nop 1
	v_mov_b32_dpp v92, v88 row_shr:1 row_mask:0xf bank_mask:0xf bound_ctrl:1
	v_mov_b32_dpp v93, v89 row_shr:1 row_mask:0xf bank_mask:0xf bound_ctrl:1
	v_pk_fma_f32 v[88:89], v[94:95], v[92:93], v[88:89]
	s_nop 1
	v_mov_b32_dpp v92, v88 row_shr:2 row_mask:0xf bank_mask:0xf bound_ctrl:1
	v_mov_b32_dpp v93, v89 row_shr:2 row_mask:0xf bank_mask:0xf bound_ctrl:1
	v_pk_fma_f32 v[88:89], v[130:131], v[92:93], v[88:89]
	s_nop 1
	v_mov_b32_dpp v92, v88 row_shr:4 row_mask:0xf bank_mask:0xf bound_ctrl:1
	v_mov_b32_dpp v93, v89 row_shr:4 row_mask:0xf bank_mask:0xf bound_ctrl:1
	v_pk_fma_f32 v[88:89], v[132:133], v[92:93], v[88:89]
	s_nop 1
	v_mov_b32_dpp v92, v88 row_shr:8 row_mask:0xf bank_mask:0xf bound_ctrl:1
	v_mov_b32_dpp v93, v89 row_shr:8 row_mask:0xf bank_mask:0xf bound_ctrl:1
	v_pk_fma_f32 v[88:89], v[134:135], v[92:93], v[88:89]
	v_mov_b32_e32 v92, 1.0
	v_pk_fma_f32 v[98:99], v[140:141], v[98:99], v[88:89]
	v_add_f32_e32 v88, v50, v128
	v_mul_f32_e32 v88, 0xbfb8aa3b, v88
	v_exp_f32_e32 v88, v88
	ds_read2_b32 v[140:141], v150 offset0:2 offset1:3
	ds_bpermute_b32 v94, v143, v98 offset:60
	ds_bpermute_b32 v95, v143, v99 offset:60
	v_add_f32_e32 v88, 1.0, v88
	v_rcp_f32_e32 v89, v88
	v_add_f32_e32 v88, v46, v124
	v_mul_f32_e32 v88, 0xbfb8aa3b, v88
	v_exp_f32_e32 v88, v88
	v_mul_f32_e32 v89, 0xc1000000, v89
	v_mul_f32_e32 v89, v2, v89
	v_mul_f32_e32 v89, 0x3fb8aa3b, v89
	v_exp_f32_e32 v124, v89
	v_add_f32_e32 v88, 1.0, v88
	v_rcp_f32_e32 v88, v88
	v_cvt_pk_bf16_f32 v98, v98, v99
	v_fma_f32 v89, -v124, v124, 1.0
	v_sqrt_f32_e32 v126, v89
	v_add_f32_e32 v89, v51, v129
	v_mul_f32_e32 v89, 0xbfb8aa3b, v89
	v_exp_f32_e32 v89, v89
	v_mov_b32_dpp v92, v124 row_shr:1 row_mask:0xf bank_mask:0xf
	v_add_f32_e32 v89, 1.0, v89
	v_rcp_f32_e32 v93, v89
	v_add_f32_e32 v89, v47, v125
	v_mul_f32_e32 v89, 0xbfb8aa3b, v89
	v_exp_f32_e32 v89, v89
	v_mul_f32_e32 v93, 0xc1000000, v93
	v_mul_f32_e32 v93, v146, v93
	v_mul_f32_e32 v93, 0x3fb8aa3b, v93
	v_exp_f32_e32 v125, v93
	v_add_f32_e32 v89, 1.0, v89
	v_rcp_f32_e32 v89, v89
	v_fma_f32 v93, -v125, v125, 1.0
	v_sqrt_f32_e32 v127, v93
	s_waitcnt lgkmcnt(0)
; __device__ __forceinline__ float sigmoidf_(float x) { return __builtin_amdgcn_rcpf(1.0f + __expf(-x)); }
; __device__ __forceinline__ float bcast15(float v, int lane) { return bperm_f((lane & 48) | 15, v); }
; __device__ __forceinline__ void w_lru_m1(const Args& a, int l, unsigned char* ws, const bf16_t* proj, bf16_t* y, LAS unsigned char* wl, int b, int ck_, int h, int lane) {
;     ...
;         for (int tb = 0; tb < 4; ++tb) { const int tok = 16 * tb + lo;
;             f32x4 ga = {0.f, 0.f, 0.f, 0.f}, gx = {0.f, 0.f, 0.f, 0.f};
; #pragma unroll
;             for (int kk = 0; kk < 2; ++kk) { ga = __builtin_amdgcn_mfma_f32_16x16x32_bf16(WaF[kk], Xf[tb][kk], ga, 0, 0, 0); gx = __builtin_amdgcn_mfma_f32_16x16x32_bf16(WxF[kk], Xf[tb][kk], gx, 0, 0, 0); }
;             float hv[4], pv[4];
; #pragma unroll
;             for (int r = 0; r < 4; ++r) {
;                 const float rg = sigmoidf_(ga[r] + bav[r]), ig = sigmoidf_(gx[r] + bxv[r]);
;                 const float la = -8.0f * rg * sp[r]; float A = __expf(la);
;                 float U = __builtin_amdgcn_sqrtf(1.0f - A * A) * (ig * xcf[tok * 65 + j0 + r]);
;                 { const float As = dpp_shr1<1>(A), Us = dpp_shr0<1>(U); U = A * Us + U; A = A * As; }
;                 { const float As = dpp_shr1<2>(A), Us = dpp_shr0<2>(U); U = A * Us + U; A = A * As; }
;                 { const float As = dpp_shr1<4>(A), Us = dpp_shr0<4>(U); U = A * Us + U; A = A * As; }
;                 { const float As = dpp_shr1<8>(A), Us = dpp_shr0<8>(U); U = A * Us + U; A = A * As; }
;                 const float hh = U + A * hc[r], PP = A * Pc[r];
;                 hc[r] = bcast15(hh, lane); Pc[r] = bcast15(PP, lane); hv[r] = hh; pv[r] = PP; }
	v_pk_mul_f32 v[88:89], v[88:89], v[140:141]
	v_mov_b32_e32 v93, 1.0
	v_pk_mul_f32 v[88:89], v[126:127], v[88:89]
	s_nop 0
	v_mov_b32_dpp v93, v125 row_shr:1 row_mask:0xf bank_mask:0xf
	v_mov_b32_dpp v126, v88 row_shr:1 row_mask:0xf bank_mask:0xf bound_ctrl:1
	v_mov_b32_dpp v127, v89 row_shr:1 row_mask:0xf bank_mask:0xf bound_ctrl:1
	v_pk_mul_f32 v[128:129], v[124:125], v[92:93]
	v_mov_b32_e32 v92, 1.0
	v_mov_b32_e32 v93, 1.0
	v_pk_fma_f32 v[88:89], v[124:125], v[126:127], v[88:89]
	v_mov_b32_dpp v92, v128 row_shr:2 row_mask:0xf bank_mask:0xf
	v_mov_b32_dpp v93, v129 row_shr:2 row_mask:0xf bank_mask:0xf
	v_mov_b32_dpp v124, v88 row_shr:2 row_mask:0xf bank_mask:0xf bound_ctrl:1
	v_mov_b32_dpp v125, v89 row_shr:2 row_mask:0xf bank_mask:0xf bound_ctrl:1
	v_pk_mul_f32 v[130:131], v[128:129], v[92:93]
	v_mov_b32_e32 v92, 1.0
	v_mov_b32_e32 v93, 1.0
	v_pk_fma_f32 v[88:89], v[128:129], v[124:125], v[88:89]
	v_mov_b32_dpp v92, v130 row_shr:4 row_mask:0xf bank_mask:0xf
	v_mov_b32_dpp v93, v131 row_shr:4 row_mask:0xf bank_mask:0xf
	v_mov_b32_dpp v124, v88 row_shr:4 row_mask:0xf bank_mask:0xf bound_ctrl:1
	v_mov_b32_dpp v125, v89 row_shr:4 row_mask:0xf bank_mask:0xf bound_ctrl:1
	v_pk_mul_f32 v[132:133], v[130:131], v[92:93]
	v_mov_b32_e32 v92, 1.0
	v_mov_b32_e32 v93, 1.0
	v_pk_fma_f32 v[88:89], v[130:131], v[124:125], v[88:89]
	v_mov_b32_dpp v92, v132 row_shr:8 row_mask:0xf bank_mask:0xf
	v_mov_b32_dpp v93, v133 row_shr:8 row_mask:0xf bank_mask:0xf
	v_mov_b32_dpp v124, v88 row_shr:8 row_mask:0xf bank_mask:0xf bound_ctrl:1
	v_mov_b32_dpp v125, v89 row_shr:8 row_mask:0xf bank_mask:0xf bound_ctrl:1
	v_pk_mul_f32 v[134:135], v[132:133], v[92:93]
	v_pk_fma_f32 v[88:89], v[132:133], v[124:125], v[88:89]
	v_or_b32_e32 v124, s48, v139
	v_pk_fma_f32 v[96:97], v[134:135], v[96:97], v[88:89]
	v_ashrrev_i32_e32 v125, 31, v124
	v_pk_mul_f32 v[90:91], v[134:135], v[90:91]
	ds_bpermute_b32 v88, v143, v96 offset:60
	ds_bpermute_b32 v89, v143, v97 offset:60
	v_cvt_pk_bf16_f32 v99, v96, v97
	v_lshlrev_b64 v[96:97], 11, v[124:125]
	ds_bpermute_b32 v92, v143, v90 offset:60
	ds_bpermute_b32 v93, v143, v91 offset:60
	v_lshl_add_u64 v[96:97], v[114:115], 0, v[96:97]
	v_cvt_pk_bf16_f32 v127, v90, v91
	v_lshlrev_b64 v[90:91], 10, v[124:125]
	v_mov_b64_e32 v[238:239], v[98:99]
	v_cvt_pk_bf16_f32 v126, v148, v149
	v_lshl_add_u64 v[98:99], v[116:117], 0, v[90:91]
	v_mov_b64_e32 v[242:243], v[126:127]
	v_mfma_f32_16x16x32_bf16 v[124:127], v[56:59], v[4:7], 0
	v_mfma_f32_16x16x32_bf16 v[56:59], v[60:63], v[20:23], v[52:55]
	v_mfma_f32_16x16x32_bf16 v[52:55], v[64:67], v[20:23], v[124:127]
	s_nop 5
	v_add_u32_e32 v124, v142, v138
	v_add_f32_e32 v48, v48, v56
	v_add_f32_e32 v49, v49, v57
	v_mul_f32_e32 v48, 0xbfb8aa3b, v48
	v_mul_f32_e32 v49, 0xbfb8aa3b, v49
	v_exp_f32_e32 v48, v48
	v_exp_f32_e32 v49, v49
	v_add_f32_e32 v44, v44, v52
	v_add_f32_e32 v45, v45, v53
	v_mul_f32_e32 v44, 0xbfb8aa3b, v44
	v_mul_f32_e32 v45, 0xbfb8aa3b, v45
	v_add_f32_e32 v48, 1.0, v48
	v_exp_f32_e32 v44, v44
	v_add_f32_e32 v49, 1.0, v49
	v_exp_f32_e32 v45, v45
	v_rcp_f32_e32 v56, v48
	v_rcp_f32_e32 v52, v49
	v_add_f32_e32 v44, 1.0, v44
	v_add_f32_e32 v45, 1.0, v45
	v_rcp_f32_e32 v48, v44
	v_mul_f32_e32 v44, 0xc1000000, v56
	v_rcp_f32_e32 v49, v45
	v_mul_f32_e32 v45, 0xc1000000, v52
	v_mul_f32_e32 v44, v145, v44
	v_mul_f32_e32 v45, v147, v45
	v_mul_f32_e32 v44, 0x3fb8aa3b, v44
	v_mul_f32_e32 v45, 0x3fb8aa3b, v45
	v_exp_f32_e32 v56, v44
	v_exp_f32_e32 v57, v45
	v_add_f32_e32 v50, v50, v58
	v_mul_f32_e32 v50, 0xbfb8aa3b, v50
	v_fma_f32 v44, -v56, v56, 1.0
	v_fma_f32 v45, -v57, v57, 1.0
	v_sqrt_f32_e32 v60, v44
	v_mov_b32_e32 v44, 1.0
	v_sqrt_f32_e32 v61, v45
	v_mov_b32_e32 v45, 1.0
	v_exp_f32_e32 v50, v50
	v_mov_b32_dpp v44, v56 row_shr:1 row_mask:0xf bank_mask:0xf
	v_mov_b32_dpp v45, v57 row_shr:1 row_mask:0xf bank_mask:0xf
	v_pk_mul_f32 v[62:63], v[56:57], v[44:45]
	v_mov_b32_e32 v44, 1.0
	v_mov_b32_e32 v45, 1.0
	v_add_f32_e32 v46, v46, v54
	v_mov_b32_dpp v44, v62 row_shr:2 row_mask:0xf bank_mask:0xf
	v_mov_b32_dpp v45, v63 row_shr:2 row_mask:0xf bank_mask:0xf
	v_mul_f32_e32 v46, 0xbfb8aa3b, v46
	v_pk_mul_f32 v[64:65], v[62:63], v[44:45]
	v_mov_b32_e32 v44, 1.0
	v_mov_b32_e32 v45, 1.0
	v_add_f32_e32 v50, 1.0, v50
	v_exp_f32_e32 v46, v46
	v_mov_b32_dpp v44, v64 row_shr:4 row_mask:0xf bank_mask:0xf
	v_mov_b32_dpp v45, v65 row_shr:4 row_mask:0xf bank_mask:0xf
	v_rcp_f32_e32 v50, v50
	v_pk_mul_f32 v[66:67], v[64:65], v[44:45]
	v_mov_b32_e32 v44, 1.0
	v_mov_b32_e32 v45, 1.0
	v_add_f32_e32 v46, 1.0, v46
	v_mov_b32_dpp v44, v66 row_shr:8 row_mask:0xf bank_mask:0xf
	v_mov_b32_dpp v45, v67 row_shr:8 row_mask:0xf bank_mask:0xf
	v_pk_mul_f32 v[90:91], v[66:67], v[44:45]
	v_rcp_f32_e32 v54, v46
	v_pk_mul_f32 v[52:53], v[90:91], v[122:123]
	ds_read2_b32 v[122:123], v124 offset1:1
	v_mul_f32_e32 v46, 0xc1000000, v50
	v_mul_f32_e32 v2, v2, v46
	v_mul_f32_e32 v2, 0x3fb8aa3b, v2
	v_exp_f32_e32 v50, v2
	s_waitcnt lgkmcnt(0)
; __device__ __forceinline__ unsigned pk2(float lo, float hi) { const f32x2_t v = {lo, hi}; const bf16x2_t b = __builtin_convertvector(v, bf16x2_t); return __builtin_bit_cast(unsigned, b); }
; __device__ __forceinline__ float sigmoidf_(float x) { return __builtin_amdgcn_rcpf(1.0f + __expf(-x)); }
; __device__ __forceinline__ float bcast15(float v, int lane) { return bperm_f((lane & 48) | 15, v); }
; __device__ __forceinline__ void w_lru_m1(const Args& a, int l, unsigned char* ws, const bf16_t* proj, bf16_t* y, LAS unsigned char* wl, int b, int ck_, int h, int lane) {
;     ...
;             for (int r = 0; r < 4; ++r) {
;                 const float rg = sigmoidf_(ga[r] + bav[r]), ig = sigmoidf_(gx[r] + bxv[r]);
;                 const float la = -8.0f * rg * sp[r]; float A = __expf(la);
;                 float U = __builtin_amdgcn_sqrtf(1.0f - A * A) * (ig * xcf[tok * 65 + j0 + r]);
;                 { const float As = dpp_shr1<1>(A), Us = dpp_shr0<1>(U); U = A * Us + U; A = A * As; }
;                 { const float As = dpp_shr1<2>(A), Us = dpp_shr0<2>(U); U = A * Us + U; A = A * As; }
;                 { const float As = dpp_shr1<4>(A), Us = dpp_shr0<4>(U); U = A * Us + U; A = A * As; }
;                 { const float As = dpp_shr1<8>(A), Us = dpp_shr0<8>(U); U = A * Us + U; A = A * As; }
;                 const float hh = U + A * hc[r], PP = A * Pc[r];
;                 hc[r] = bcast15(hh, lane); Pc[r] = bcast15(PP, lane); hv[r] = hh; pv[r] = PP; }
;             *(unsigned long long*)(y + (size_t)(row0 + tok) * DM + 64 * h + j0) = (unsigned long long)pk2(hv[0], hv[1]) | ((unsigned long long)pk2(hv[2], hv[3]) << 32);
;             *(unsigned long long*)((bf16_t*)(ws + WS_P) + (size_t)(row0 + tok) * 512 + 64 * h + j0) = (unsigned long long)pk2(pv[0], pv[1]) | ((unsigned long long)pk2(pv[2], pv[3]) << 32);
;         }
;         if (lo == 0) { const size_t so = (size_t)(b * NCH + ck_) * 512 + 64 * h + j0;
; #pragma unroll
;             for (int r = 0; r < 4; ++r) { ((float*)(ws + WS_LRUA))[so + r] = Pc[r]; ((float*)(ws + WS_LRUH))[so + r] = hc[r]; } }
	v_pk_mul_f32 v[48:49], v[122:123], v[48:49]
	v_add_f32_e32 v47, v47, v55
	v_pk_mul_f32 v[48:49], v[48:49], v[60:61]
	v_fma_f32 v2, -v50, v50, 1.0
	v_mul_f32_e32 v47, 0xbfb8aa3b, v47
	v_mov_b32_dpp v60, v48 row_shr:1 row_mask:0xf bank_mask:0xf bound_ctrl:1
	v_mov_b32_dpp v61, v49 row_shr:1 row_mask:0xf bank_mask:0xf bound_ctrl:1
	v_pk_fma_f32 v[48:49], v[56:57], v[60:61], v[48:49]
	v_sqrt_f32_e32 v60, v2
	v_add_f32_e32 v2, v51, v59
	v_mul_f32_e32 v2, 0xbfb8aa3b, v2
	v_exp_f32_e32 v2, v2
	v_exp_f32_e32 v47, v47
	v_mov_b32_e32 v46, 1.0
	v_mov_b32_dpp v56, v48 row_shr:2 row_mask:0xf bank_mask:0xf bound_ctrl:1
	v_add_f32_e32 v2, 1.0, v2
	v_rcp_f32_e32 v2, v2
	v_add_f32_e32 v47, 1.0, v47
	v_rcp_f32_e32 v55, v47
	v_mov_b32_e32 v47, 1.0
	v_mul_f32_e32 v2, 0xc1000000, v2
	v_mul_f32_e32 v2, v146, v2
	v_mul_f32_e32 v2, 0x3fb8aa3b, v2
	v_exp_f32_e32 v51, v2
	v_mov_b32_dpp v57, v49 row_shr:2 row_mask:0xf bank_mask:0xf bound_ctrl:1
	v_mov_b32_dpp v46, v50 row_shr:1 row_mask:0xf bank_mask:0xf
	v_pk_fma_f32 v[48:49], v[62:63], v[56:57], v[48:49]
	v_mov_b32_dpp v47, v51 row_shr:1 row_mask:0xf bank_mask:0xf
	v_pk_mul_f32 v[62:63], v[50:51], v[46:47]
	v_mov_b32_e32 v46, 1.0
	v_mov_b32_e32 v47, 1.0
	v_mov_b32_dpp v56, v48 row_shr:4 row_mask:0xf bank_mask:0xf bound_ctrl:1
	v_mov_b32_dpp v57, v49 row_shr:4 row_mask:0xf bank_mask:0xf bound_ctrl:1
	v_mov_b32_dpp v46, v62 row_shr:2 row_mask:0xf bank_mask:0xf
	v_mov_b32_dpp v47, v63 row_shr:2 row_mask:0xf bank_mask:0xf
	v_pk_fma_f32 v[48:49], v[64:65], v[56:57], v[48:49]
	v_pk_mul_f32 v[64:65], v[62:63], v[46:47]
	v_mov_b32_e32 v46, 1.0
	v_mov_b32_e32 v47, 1.0
	v_mov_b32_dpp v56, v48 row_shr:8 row_mask:0xf bank_mask:0xf bound_ctrl:1
	v_mov_b32_dpp v57, v49 row_shr:8 row_mask:0xf bank_mask:0xf bound_ctrl:1
	v_mov_b32_dpp v46, v64 row_shr:4 row_mask:0xf bank_mask:0xf
	v_mov_b32_dpp v47, v65 row_shr:4 row_mask:0xf bank_mask:0xf
	v_pk_fma_f32 v[48:49], v[66:67], v[56:57], v[48:49]
	v_pk_mul_f32 v[66:67], v[64:65], v[46:47]
	v_mov_b32_e32 v46, 1.0
	v_mov_b32_e32 v47, 1.0
	v_pk_fma_f32 v[56:57], v[90:91], v[94:95], v[48:49]
	v_mov_b32_dpp v46, v66 row_shr:8 row_mask:0xf bank_mask:0xf
	v_mov_b32_dpp v47, v67 row_shr:8 row_mask:0xf bank_mask:0xf
	v_pk_mul_f32 v[90:91], v[66:67], v[46:47]
	v_fma_f32 v2, -v51, v51, 1.0
	v_pk_mul_f32 v[58:59], v[90:91], v[92:93]
	ds_read2_b32 v[92:93], v124 offset0:2 offset1:3
	v_sqrt_f32_e32 v61, v2
	ds_bpermute_b32 v44, v143, v52 offset:60
	ds_bpermute_b32 v48, v143, v56 offset:60
	ds_bpermute_b32 v49, v143, v57 offset:60
	s_waitcnt lgkmcnt(0)
	v_pk_mul_f32 v[54:55], v[54:55], v[92:93]
	ds_bpermute_b32 v45, v143, v53 offset:60
	v_pk_mul_f32 v[54:55], v[60:61], v[54:55]
	ds_bpermute_b32 v46, v143, v58 offset:60
	ds_bpermute_b32 v47, v143, v59 offset:60
	v_mov_b32_dpp v60, v54 row_shr:1 row_mask:0xf bank_mask:0xf bound_ctrl:1
	v_mov_b32_dpp v61, v55 row_shr:1 row_mask:0xf bank_mask:0xf bound_ctrl:1
	v_pk_fma_f32 v[50:51], v[50:51], v[60:61], v[54:55]
	v_cvt_pk_bf16_f32 v56, v56, v57
	v_cvt_pk_bf16_f32 v52, v52, v53
	v_mov_b32_dpp v54, v50 row_shr:2 row_mask:0xf bank_mask:0xf bound_ctrl:1
	v_mov_b32_dpp v55, v51 row_shr:2 row_mask:0xf bank_mask:0xf bound_ctrl:1
	v_pk_fma_f32 v[50:51], v[62:63], v[54:55], v[50:51]
	v_cvt_pk_bf16_f32 v53, v58, v59
	s_nop 0
	v_mov_b32_dpp v54, v50 row_shr:4 row_mask:0xf bank_mask:0xf bound_ctrl:1
	v_mov_b32_dpp v55, v51 row_shr:4 row_mask:0xf bank_mask:0xf bound_ctrl:1
	v_pk_fma_f32 v[50:51], v[64:65], v[54:55], v[50:51]
	s_nop 1
	v_mov_b32_dpp v54, v50 row_shr:8 row_mask:0xf bank_mask:0xf bound_ctrl:1
	v_mov_b32_dpp v55, v51 row_shr:8 row_mask:0xf bank_mask:0xf bound_ctrl:1
	v_pk_fma_f32 v[50:51], v[66:67], v[54:55], v[50:51]
	s_nop 0
	v_pk_fma_f32 v[54:55], v[90:91], v[88:89], v[50:51]
	ds_bpermute_b32 v50, v143, v54 offset:60
	ds_bpermute_b32 v51, v143, v55 offset:60
	v_cvt_pk_bf16_f32 v57, v54, v55
	v_or_b32_e32 v54, s48, v137
	v_ashrrev_i32_e32 v55, 31, v54
	v_lshlrev_b64 v[60:61], 11, v[54:55]
	v_lshlrev_b64 v[54:55], 10, v[54:55]
	v_lshl_add_u64 v[114:115], v[114:115], 0, v[60:61]
	v_lshl_add_u64 v[116:117], v[116:117], 0, v[54:55]
	v_mov_b64_e32 v[246:247], v[56:57]
	v_mov_b64_e32 v[250:251], v[52:53]
	s_and_saveexec_b64 s[34:35], vcc
	s_cbranch_execz .LBB0_523
	v_lshl_add_u64 v[52:53], s[42:43], 0, v[0:1]
	v_lshlrev_b64 v[52:53], 2, v[52:53]
	v_lshl_add_u64 v[54:55], s[84:85], 0, v[52:53]
	v_lshl_add_u64 v[52:53], s[86:87], 0, v[52:53]
	s_waitcnt lgkmcnt(0)
	global_store_dwordx4 v[54:55], v[44:47], off
	global_store_dwordx4 v[52:53], v[48:51], off
